# NSA region: hipcc's SLP-packed v_pk_add/mul/fma_f32 split into scalar f32 ops (asm guide 7.5)
# baseline (speedup 1.0000x reference)
; #define LAS __attribute__((address_space(3)))
; #define MFMA32(a, b, c) __builtin_amdgcn_mfma_f32_32x32x16_bf16((a), (b), (c), 0, 0, 0)
; __device__ __forceinline__ void nsa_unit(const Frame& F, int plane, int qt) {
;     ...
;     const int lane = F.lane, r = lane & 31, h = lane >> 5, w = F.wave;
;     const int b = plane >> 1, kvh = plane & 1, g = r & 3, head = kvh * 4 + g;
;     const int t = qt * 64 + w * 8 + (r >> 2), cur = qt;
;     const size_t tok = (size_t)b * S + t;
;     const size_t qoff = (((size_t)b * 8 + head) * S + t) * 64 + 8 * h;
;     const float* ng = (const float*)(F.ws + WS_NG) + tok * 24 + head * 3;
;     const float gate_c = ng[0], gate_s = ng[1], gate_w = ng[2];
;     unsigned selmask = 0u;
;     __syncthreads();
;     { const int row = F.tid >> 2, part = F.tid & 3;
;       const u32x4* src = (const u32x4*)((const bf16*)(F.ws + WS_KCB) + ((size_t)plane * 128 + row) * 64 + part * 16);
;       *(LAS u32x4*)(L + NL_KC + row * 144 + part * 32) = src[0]; *(LAS u32x4*)(L + NL_KC + row * 144 + part * 32 + 16) = src[1];
;       const int d = F.tid >> 3, p8 = F.tid & 7;
;       const u32x4* sv = (const u32x4*)((const bf16*)(F.ws + WS_VCT) + ((size_t)plane * 64 + d) * 128 + p8 * 16);
;       *(LAS u32x4*)(L + NL_VC + d * 272 + p8 * 32) = sv[0]; *(LAS u32x4*)(L + NL_VC + d * 272 + p8 * 32 + 16) = sv[1]; }
;     __syncthreads();
;     {
;         bf16x8 qu[4];
; #pragma unroll
;         for (int ks = 0; ks < 4; ++ks) qu[ks] = *(const bf16x8*)((const bf16*)(F.ws + WS_NQU) + qoff + 16 * ks);
;         const int cmax = (t - 31) >> 4;
;         float mx = -1e20f;
; #pragma unroll
;         for (int ct = 0; ct < 4; ++ct) {
;             f32x16 sc;
; #pragma unroll
;             for (int i = 0; i < 16; ++i) sc[i] = 0.f;
; #pragma unroll
;             for (int ks = 0; ks < 4; ++ks) { const bf16x8 a = *(const LAS bf16x8*)(L + NL_KC + (32 * ct + r) * 144 + (16 * ks + 8 * h) * 2); sc = MFMA32(a, qu[ks], sc); }
.LBB0_1751:
	v_mov_b32_e32 v1, v0
	v_readlane_b32 s40, v251, 0
	v_readlane_b32 s41, v251, 1
	v_readfirstlane_b32 s0, v1
	s_ashr_i32 s5, s0, 6
	s_mov_b64 s[28:29], s[78:79]
	s_mov_b64 s[0:1], s[40:41]
	s_and_b32 s3, s6, 15
	s_lshr_b32 s4, s6, 4
	s_bfe_u32 s9, s6, 0x40004
	s_xor_b32 s0, s3, 31
	s_cmpk_lt_i32 s6, 0x100
	s_cselect_b32 s8, s3, s0
	s_waitcnt vmcnt(0)
	v_and_b32_e32 v6, 3, v1
	s_lshr_b32 s1, s6, 2
	v_and_or_b32 v161, s1, 4, v6
	s_lshl_b32 s7, s8, 6
	s_lshl_b32 s1, s5, 3
	s_add_i32 s1, s1, s7
	s_waitcnt vmcnt(15)
	v_bfe_u32 v2, v1, 2, 3
	s_bfe_u32 s0, s4, 0x30001
	s_waitcnt vmcnt(2)
	v_or_b32_e32 v128, s1, v2
	s_lshl_b32 s34, s0, 11
	v_ashrrev_i32_e32 v129, 31, v128
	v_lshl_add_u64 v[126:127], s[34:35], 0, v[128:129]
	v_lshlrev_b32_e32 v2, 11, v161
	v_mov_b64_e32 v[4:5], s[28:29]
	s_movk_i32 s3, 0x60
	v_lshl_or_b32 v198, s0, 14, v2
	v_mad_u64_u32 v[4:5], s[0:1], v126, s3, v[4:5]
	v_mul_u32_u24_e32 v7, 3, v161
	v_lshl_add_u64 v[2:3], v[198:199], 0, v[128:129]
	v_mad_i32_i24 v5, v127, s3, v5
	v_lshlrev_b32_e32 v198, 2, v7
	v_lshl_add_u64 v[4:5], v[4:5], 0, v[198:199]
	s_mov_b32 s0, 0x6f000000
	v_add_co_u32_e32 v4, vcc, s0, v4
	v_ashrrev_i32_e32 v12, 2, v1
	s_lshl_b32 s0, s9, 14
	v_addc_co_u32_e32 v5, vcc, 0, v5, vcc
	v_ashrrev_i32_e32 v13, 31, v12
	s_add_u32 s0, s28, s0
	global_load_dwordx3 v[122:124], v[4:5], off
	v_lshlrev_b64 v[4:5], 7, v[12:13]
	s_addc_u32 s1, s29, 0
	v_lshl_add_u64 v[4:5], s[0:1], 0, v[4:5]
	v_lshlrev_b32_e32 v198, 5, v6
	v_lshl_add_u64 v[4:5], v[4:5], 0, v[198:199]
	s_mov_b64 s[10:11], 0x6fc00000
	s_mov_b32 s3, 0x6fc00000
	v_lshl_add_u64 v[8:9], v[4:5], 0, s[10:11]
	v_add_co_u32_e32 v4, vcc, s3, v4
	s_nop 1
	v_addc_co_u32_e32 v5, vcc, 0, v5, vcc
	s_barrier
	global_load_dwordx4 v[4:7], v[4:5], off
	s_nop 0
	global_load_dwordx4 v[8:11], v[8:9], off offset:16
	s_movk_i32 s10, 0x90
	v_mul_lo_u32 v12, v12, s10
	s_waitcnt vmcnt(4)
	v_ashrrev_i32_e32 v130, 3, v1
	v_add3_u32 v12, 0, v12, v198
	v_ashrrev_i32_e32 v131, 31, v130
	v_and_b32_e32 v114, 7, v1
	v_mov_b32_e32 v13, v199
	s_movk_i32 s11, 0x110
	v_and_b32_e32 v14, 63, v1
	v_and_b32_e32 v83, 31, v1
	v_bfe_u32 v1, v1, 5, 1
	v_lshlrev_b64 v[2:3], 6, v[2:3]
	v_lshlrev_b32_e32 v206, 3, v1
	v_or_b32_e32 v2, v2, v206
	s_waitcnt vmcnt(3)
	v_lshl_add_u64 v[66:67], v[2:3], 1, s[28:29]
	v_lshlrev_b32_e32 v97, 4, v1
	v_add_u32_e32 v19, 0, v97
	v_mad_u32_u24 v100, v83, s10, v19
	v_lshlrev_b32_e32 v204, 2, v1
	s_mov_b32 s14, 8
	v_lshlrev_b32_e32 v198, 4, v114
	v_mul_u32_u24_e32 v96, 0x90, v83
	s_movk_i32 s3, 0x90
	v_or_b32_e32 v68, 2, v1
	v_or_b32_e32 v69, 24, v1
	v_or_b32_e32 v70, 26, v1
	v_or_b32_e32 v71, 20, v1
	v_or_b32_e32 v72, 22, v1
	v_or_b32_e32 v73, 16, v1
	v_or_b32_e32 v74, 18, v1
	v_or_b32_e32 v75, 12, v1
	v_or_b32_e32 v76, 14, v1
	v_or_b32_e32 v77, 8, v1
	v_or_b32_e32 v78, 10, v1
	v_readlane_b32 s42, v251, 2
	v_readlane_b32 s43, v251, 3
	s_waitcnt vmcnt(1)
	ds_write_b128 v12, v[4:7]
	s_waitcnt vmcnt(0)
	ds_write_b128 v12, v[8:11] offset:16
	v_lshlrev_b64 v[4:5], 8, v[130:131]
	v_lshl_add_u64 v[4:5], s[0:1], 0, v[4:5]
	v_lshlrev_b32_e32 v12, 5, v114
	v_lshl_add_u64 v[4:5], v[4:5], 0, v[12:13]
	s_mov_b64 s[0:1], 0x6fd00000
	v_lshl_add_u64 v[8:9], v[4:5], 0, s[0:1]
	s_mov_b32 s0, 0x6fd00000
	v_add_co_u32_e32 v4, vcc, s0, v4
	v_mul_lo_u32 v13, v130, s11
	s_nop 0
	v_addc_co_u32_e32 v5, vcc, 0, v5, vcc
	global_load_dwordx4 v[4:7], v[4:5], off
	s_nop 0
	global_load_dwordx4 v[8:11], v[8:9], off offset:16
	v_add3_u32 v12, 0, v13, v12
	s_lshl_b32 s0, s5, 13
	s_add_i32 s0, s0, 0
	v_lshl_add_u32 v203, v14, 2, s0
	s_waitcnt vmcnt(1)
	ds_write_b128 v12, v[4:7] offset:18432
	s_waitcnt vmcnt(0)
	ds_write_b128 v12, v[8:11] offset:18448
	v_subrev_u32_e32 v4, 31, v128
	v_and_b32_e32 v5, 64, v225
	v_ashrrev_i32_e32 v18, 4, v4
	v_xor_b32_e32 v4, 32, v225
	v_add_u32_e32 v5, 64, v5
	v_cmp_lt_i32_e32 vcc, v4, v5
	s_waitcnt lgkmcnt(0)
	s_barrier
	v_cndmask_b32_e32 v4, v225, v4, vcc
	v_lshlrev_b32_e32 v205, 2, v4
	v_xor_b32_e32 v4, 1, v225
	v_cmp_lt_i32_e64 s[0:1], v4, v5
	v_cmp_gt_u32_e32 vcc, 32, v14
	s_nop 0
	v_cndmask_b32_e64 v4, v225, v4, s[0:1]
	v_lshlrev_b32_e32 v99, 2, v4
	v_xor_b32_e32 v4, 2, v225
	v_cmp_lt_i32_e64 s[0:1], v4, v5
	s_nop 1
	v_cndmask_b32_e64 v4, v225, v4, s[0:1]
	s_mov_b64 s[0:1], 0x6b800000
	v_lshl_add_u64 v[2:3], v[66:67], 0, s[0:1]
	s_mov_b32 s0, 0x6b800000
	v_lshlrev_b32_e32 v98, 2, v4
	v_add_co_u32_e64 v4, s[0:1], s0, v66
	s_nop 1
	v_addc_co_u32_e64 v5, s[0:1], 0, v67, s[0:1]
	global_load_dwordx4 v[58:61], v[4:5], off
	global_load_dwordx4 v[54:57], v[2:3], off offset:32
	global_load_dwordx4 v[50:53], v[2:3], off offset:64
	global_load_dwordx4 v[62:65], v[2:3], off offset:96
	ds_read_b128 v[2:5], v100
	ds_read_b128 v[20:23], v100 offset:32
	v_cmp_lt_i32_e64 s[0:1], v18, v204
	s_waitcnt vmcnt(3) lgkmcnt(1)
	v_mfma_f32_32x32x16_bf16 v[2:17], v[2:5], v[58:61], 0
	ds_read_b128 v[36:39], v100 offset:4640
	s_waitcnt vmcnt(2) lgkmcnt(1)
	v_mfma_f32_32x32x16_bf16 v[2:17], v[20:23], v[54:57], v[2:17]
	ds_read_b128 v[20:23], v100 offset:64
	s_waitcnt vmcnt(1) lgkmcnt(0)
	v_mfma_f32_32x32x16_bf16 v[2:17], v[20:23], v[50:53], v[2:17]
	ds_read_b128 v[20:23], v100 offset:96
	s_waitcnt vmcnt(0) lgkmcnt(0)
; #define LAS __attribute__((address_space(3)))
; #define MFMA32(a, b, c) __builtin_amdgcn_mfma_f32_32x32x16_bf16((a), (b), (c), 0, 0, 0)
; __device__ __forceinline__ void nsa_unit(const Frame& F, int plane, int qt) {
;     ...
; #pragma unroll
;         for (int ct = 0; ct < 4; ++ct) {
;             f32x16 sc;
; #pragma unroll
;             for (int i = 0; i < 16; ++i) sc[i] = 0.f;
; #pragma unroll
;             for (int ks = 0; ks < 4; ++ks) { const bf16x8 a = *(const LAS bf16x8*)(L + NL_KC + (32 * ct + r) * 144 + (16 * ks + 8 * h) * 2); sc = MFMA32(a, qu[ks], sc); }
; #pragma unroll
;             for (int i = 0; i < 16; ++i) { const int c = 32 * ct + (i & 3) + 8 * (i >> 2) + 4 * h; mx = fmaxf(mx, sc[i] + __int_as_float(((cmax - c) >> 31) & (int)0xF149F2CA)); }
;         }
	v_mfma_f32_32x32x16_bf16 v[2:17], v[20:23], v[62:65], v[2:17]
	v_cndmask_b32_e64 v20, 0, v234, s[0:1]
	v_cmp_gt_i32_e64 s[0:1], v18, v204
	s_nop 9
	v_add_f32_e32 v20, v2, v20
	v_cndmask_b32_e64 v2, v234, 0, s[0:1]
	v_add_f32_e32 v21, v3, v2
	s_mov_b32 s0, 0xe0ad78ec
	v_or_b32_e32 v3, 2, v204
	v_max3_f32 v2, v20, s0, v21
	v_cmp_lt_i32_e64 s[0:1], v18, v3
	s_nop 1
	v_cndmask_b32_e64 v3, 0, v234, s[0:1]
	v_add_f32_e32 v22, v4, v3
	v_or_b32_e32 v3, 3, v204
	v_cmp_lt_i32_e64 s[0:1], v18, v3
	s_nop 1
	v_cndmask_b32_e64 v3, 0, v234, s[0:1]
	v_add_f32_e32 v23, v5, v3
	v_or_b32_e32 v3, 8, v204
	v_cmp_lt_i32_e64 s[0:1], v18, v3
	v_max3_f32 v2, v2, v22, v23
	s_nop 0
	v_cndmask_b32_e64 v3, 0, v234, s[0:1]
	v_add_f32_e32 v24, v6, v3
	v_or_b32_e32 v3, 9, v204
	v_cmp_lt_i32_e64 s[0:1], v18, v3
	s_nop 1
	v_cndmask_b32_e64 v3, 0, v234, s[0:1]
	v_add_f32_e32 v25, v7, v3
	v_or_b32_e32 v3, 10, v204
	v_cmp_lt_i32_e64 s[0:1], v18, v3
	v_max3_f32 v2, v2, v24, v25
	s_nop 0
	v_cndmask_b32_e64 v3, 0, v234, s[0:1]
	v_add_f32_e32 v26, v8, v3
	v_or_b32_e32 v3, 11, v204
	v_cmp_lt_i32_e64 s[0:1], v18, v3
	s_nop 1
	v_cndmask_b32_e64 v3, 0, v234, s[0:1]
	v_add_f32_e32 v27, v9, v3
	v_or_b32_e32 v3, 16, v204
	v_cmp_lt_i32_e64 s[0:1], v18, v3
	v_max3_f32 v2, v2, v26, v27
	s_nop 0
	v_cndmask_b32_e64 v3, 0, v234, s[0:1]
	v_add_f32_e32 v28, v10, v3
	v_or_b32_e32 v3, 17, v204
	v_cmp_lt_i32_e64 s[0:1], v18, v3
	s_nop 1
	v_cndmask_b32_e64 v3, 0, v234, s[0:1]
	v_add_f32_e32 v29, v11, v3
	v_or_b32_e32 v3, 18, v204
	v_cmp_lt_i32_e64 s[0:1], v18, v3
	v_max3_f32 v2, v2, v28, v29
	s_nop 0
	v_cndmask_b32_e64 v3, 0, v234, s[0:1]
	v_add_f32_e32 v30, v12, v3
	v_or_b32_e32 v3, 19, v204
	v_cmp_lt_i32_e64 s[0:1], v18, v3
	s_nop 1
	v_cndmask_b32_e64 v3, 0, v234, s[0:1]
	v_add_f32_e32 v31, v13, v3
	v_or_b32_e32 v3, 24, v204
	v_cmp_lt_i32_e64 s[0:1], v18, v3
	v_max3_f32 v2, v2, v30, v31
	s_nop 0
	v_cndmask_b32_e64 v3, 0, v234, s[0:1]
	v_add_f32_e32 v32, v14, v3
	v_or_b32_e32 v3, 25, v204
	v_cmp_lt_i32_e64 s[0:1], v18, v3
	s_nop 1
	v_cndmask_b32_e64 v3, 0, v234, s[0:1]
	v_add_f32_e32 v33, v15, v3
	v_or_b32_e32 v3, 26, v204
	v_cmp_lt_i32_e64 s[0:1], v18, v3
	v_max3_f32 v2, v2, v32, v33
	s_nop 0
	v_cndmask_b32_e64 v3, 0, v234, s[0:1]
	v_add_f32_e32 v34, v16, v3
	v_or_b32_e32 v3, 27, v204
	v_cmp_lt_i32_e64 s[0:1], v18, v3
	s_nop 1
	v_cndmask_b32_e64 v3, 0, v234, s[0:1]
	v_add_f32_e32 v42, v17, v3
	v_max3_f32 v35, v2, v34, v42
	ds_read_b128 v[2:5], v100 offset:4608
	s_waitcnt lgkmcnt(0)
	v_mfma_f32_32x32x16_bf16 v[2:17], v[2:5], v[58:61], 0
	v_mfma_f32_32x32x16_bf16 v[2:17], v[36:39], v[54:57], v[2:17]
	ds_read_b128 v[36:39], v100 offset:4672
	s_waitcnt lgkmcnt(0)
	v_mfma_f32_32x32x16_bf16 v[2:17], v[36:39], v[50:53], v[2:17]
	ds_read_b128 v[36:39], v100 offset:4704
	s_waitcnt lgkmcnt(0)
	v_mfma_f32_32x32x16_bf16 v[2:17], v[36:39], v[62:65], v[2:17]
	v_or_b32_e32 v36, 32, v204
	v_cmp_lt_i32_e64 s[0:1], v18, v36
	s_nop 1
	v_cndmask_b32_e64 v82, 0, v234, s[0:1]
	v_cmp_gt_i32_e64 s[0:1], v18, v36
	ds_read_b128 v[36:39], v100 offset:9248
	s_nop 4
	v_add_f32_e32 v2, v2, v82
	v_cndmask_b32_e64 v79, v234, 0, s[0:1]
	v_add_f32_e32 v3, v3, v79
	v_max3_f32 v2, v35, v2, v3
	v_or_b32_e32 v3, 34, v204
	v_cmp_lt_i32_e64 s[0:1], v18, v3
	s_nop 1
	v_cndmask_b32_e64 v93, 0, v234, s[0:1]
	v_add_f32_e32 v3, v4, v93
	v_or_b32_e32 v4, 35, v204
	v_cmp_lt_i32_e64 s[0:1], v18, v4
	s_nop 1
	v_cndmask_b32_e64 v95, 0, v234, s[0:1]
	v_add_f32_e32 v4, v5, v95
	v_max3_f32 v2, v2, v3, v4
	v_or_b32_e32 v3, 40, v204
	v_cmp_lt_i32_e64 s[0:1], v18, v3
	v_or_b32_e32 v4, 41, v204
	s_nop 0
	v_cndmask_b32_e64 v86, 0, v234, s[0:1]
	v_cmp_lt_i32_e64 s[0:1], v18, v4
	v_add_f32_e32 v3, v6, v86
	s_nop 0
	v_cndmask_b32_e64 v90, 0, v234, s[0:1]
	v_add_f32_e32 v4, v7, v90
	v_max3_f32 v2, v2, v3, v4
	v_or_b32_e32 v3, 42, v204
	v_cmp_lt_i32_e64 s[0:1], v18, v3
	v_or_b32_e32 v4, 43, v204
	s_nop 0
	v_cndmask_b32_e64 v92, 0, v234, s[0:1]
	v_cmp_lt_i32_e64 s[0:1], v18, v4
	v_add_f32_e32 v3, v8, v92
	s_nop 0
	v_cndmask_b32_e64 v94, 0, v234, s[0:1]
	v_add_f32_e32 v4, v9, v94
	v_max3_f32 v2, v2, v3, v4
	v_or_b32_e32 v3, 48, v204
	v_cmp_lt_i32_e64 s[0:1], v18, v3
	v_or_b32_e32 v4, 49, v204
	s_nop 0
	v_cndmask_b32_e64 v150, 0, v234, s[0:1]
	v_cmp_lt_i32_e64 s[0:1], v18, v4
	v_add_f32_e32 v3, v10, v150
	s_nop 0
	v_cndmask_b32_e64 v149, 0, v234, s[0:1]
	v_add_f32_e32 v4, v11, v149
	v_max3_f32 v2, v2, v3, v4
	v_or_b32_e32 v3, 50, v204
	v_cmp_lt_i32_e64 s[0:1], v18, v3
	v_or_b32_e32 v4, 51, v204
	s_nop 0
	v_cndmask_b32_e64 v148, 0, v234, s[0:1]
	v_cmp_lt_i32_e64 s[0:1], v18, v4
	v_add_f32_e32 v3, v12, v148
	s_nop 0
	v_cndmask_b32_e64 v147, 0, v234, s[0:1]
	v_add_f32_e32 v4, v13, v147
	v_max3_f32 v2, v2, v3, v4
	v_or_b32_e32 v3, 56, v204
	v_cmp_lt_i32_e64 s[0:1], v18, v3
	v_or_b32_e32 v4, 57, v204
	s_nop 0
	v_cndmask_b32_e64 v88, 0, v234, s[0:1]
	v_cmp_lt_i32_e64 s[0:1], v18, v4
	v_add_f32_e32 v3, v14, v88
	s_nop 0
	v_cndmask_b32_e64 v89, 0, v234, s[0:1]
	v_add_f32_e32 v4, v15, v89
	v_max3_f32 v2, v2, v3, v4
	v_or_b32_e32 v3, 58, v204
	v_cmp_lt_i32_e64 s[0:1], v18, v3
	v_or_b32_e32 v4, 59, v204
	s_nop 0
	v_cndmask_b32_e64 v143, 0, v234, s[0:1]
	v_cmp_lt_i32_e64 s[0:1], v18, v4
	v_add_f32_e32 v3, v16, v143
	s_nop 0
	v_cndmask_b32_e64 v144, 0, v234, s[0:1]
	v_add_f32_e32 v4, v17, v144
	v_max3_f32 v35, v2, v3, v4
	ds_read_b128 v[2:5], v100 offset:9216
	s_waitcnt lgkmcnt(0)
	v_mfma_f32_32x32x16_bf16 v[2:17], v[2:5], v[58:61], 0
	v_mfma_f32_32x32x16_bf16 v[2:17], v[36:39], v[54:57], v[2:17]
	ds_read_b128 v[36:39], v100 offset:9280
	s_waitcnt lgkmcnt(0)
	v_mfma_f32_32x32x16_bf16 v[2:17], v[36:39], v[50:53], v[2:17]
	ds_read_b128 v[36:39], v100 offset:9312
	s_waitcnt lgkmcnt(0)
; #define LAS __attribute__((address_space(3)))
; #define MFMA32(a, b, c) __builtin_amdgcn_mfma_f32_32x32x16_bf16((a), (b), (c), 0, 0, 0)
; __device__ __forceinline__ void nsa_unit(const Frame& F, int plane, int qt) {
;     ...
;         for (int ct = 0; ct < 4; ++ct) {
;             f32x16 sc;
; #pragma unroll
;             for (int i = 0; i < 16; ++i) sc[i] = 0.f;
; #pragma unroll
;             for (int ks = 0; ks < 4; ++ks) { const bf16x8 a = *(const LAS bf16x8*)(L + NL_KC + (32 * ct + r) * 144 + (16 * ks + 8 * h) * 2); sc = MFMA32(a, qu[ks], sc); }
; #pragma unroll
;             for (int i = 0; i < 16; ++i) { const int c = 32 * ct + (i & 3) + 8 * (i >> 2) + 4 * h; mx = fmaxf(mx, sc[i] + __int_as_float(((cmax - c) >> 31) & (int)0xF149F2CA)); }
;         }
;         mx = fmaxf(mx, __shfl_xor(mx, 32));
	v_mfma_f32_32x32x16_bf16 v[2:17], v[36:39], v[62:65], v[2:17]
	v_or_b32_e32 v36, 64, v204
	v_cmp_lt_i32_e64 s[0:1], v18, v36
	s_nop 1
	v_cndmask_b32_e64 v105, 0, v234, s[0:1]
	v_cmp_gt_i32_e64 s[0:1], v18, v36
	ds_read_b128 v[36:39], v100 offset:13856
	s_nop 4
	v_add_f32_e32 v2, v2, v105
	v_cndmask_b32_e64 v104, v234, 0, s[0:1]
	v_add_f32_e32 v3, v3, v104
	v_max3_f32 v2, v35, v2, v3
	v_or_b32_e32 v3, 0x42, v204
	v_cmp_lt_i32_e64 s[0:1], v18, v3
	s_nop 1
	v_cndmask_b32_e64 v106, 0, v234, s[0:1]
	v_add_f32_e32 v3, v4, v106
	v_or_b32_e32 v4, 0x43, v204
	v_cmp_lt_i32_e64 s[0:1], v18, v4
	s_nop 1
	v_cndmask_b32_e64 v107, 0, v234, s[0:1]
	v_add_f32_e32 v4, v5, v107
	v_max3_f32 v2, v2, v3, v4
	v_or_b32_e32 v3, 0x48, v204
	v_cmp_lt_i32_e64 s[0:1], v18, v3
	v_or_b32_e32 v4, 0x49, v204
	s_nop 0
	v_cndmask_b32_e64 v108, 0, v234, s[0:1]
	v_cmp_lt_i32_e64 s[0:1], v18, v4
	v_add_f32_e32 v3, v6, v108
	s_nop 0
	v_cndmask_b32_e64 v109, 0, v234, s[0:1]
	v_add_f32_e32 v4, v7, v109
	v_max3_f32 v2, v2, v3, v4
	v_or_b32_e32 v3, 0x4a, v204
	v_cmp_lt_i32_e64 s[0:1], v18, v3
	v_or_b32_e32 v4, 0x4b, v204
	s_nop 0
	v_cndmask_b32_e64 v110, 0, v234, s[0:1]
	v_cmp_lt_i32_e64 s[0:1], v18, v4
	v_add_f32_e32 v3, v8, v110
	s_nop 0
	v_cndmask_b32_e64 v111, 0, v234, s[0:1]
	v_add_f32_e32 v4, v9, v111
	v_max3_f32 v2, v2, v3, v4
	v_or_b32_e32 v3, 0x50, v204
	v_cmp_lt_i32_e64 s[0:1], v18, v3
	v_or_b32_e32 v4, 0x51, v204
	s_nop 0
	v_cndmask_b32_e64 v112, 0, v234, s[0:1]
	v_cmp_lt_i32_e64 s[0:1], v18, v4
	v_add_f32_e32 v3, v10, v112
	s_nop 0
	v_cndmask_b32_e64 v113, 0, v234, s[0:1]
	v_add_f32_e32 v4, v11, v113
	v_max3_f32 v2, v2, v3, v4
	v_or_b32_e32 v3, 0x52, v204
	v_cmp_lt_i32_e64 s[0:1], v18, v3
	v_or_b32_e32 v4, 0x53, v204
	s_nop 0
	v_cndmask_b32_e64 v115, 0, v234, s[0:1]
	v_cmp_lt_i32_e64 s[0:1], v18, v4
	v_add_f32_e32 v3, v12, v115
	s_nop 0
	v_cndmask_b32_e64 v116, 0, v234, s[0:1]
	v_add_f32_e32 v4, v13, v116
	v_max3_f32 v2, v2, v3, v4
	v_or_b32_e32 v3, 0x58, v204
	v_cmp_lt_i32_e64 s[0:1], v18, v3
	v_or_b32_e32 v4, 0x59, v204
	s_nop 0
	v_cndmask_b32_e64 v117, 0, v234, s[0:1]
	v_cmp_lt_i32_e64 s[0:1], v18, v4
	v_add_f32_e32 v3, v14, v117
	s_nop 0
	v_cndmask_b32_e64 v101, 0, v234, s[0:1]
	v_add_f32_e32 v4, v15, v101
	v_max3_f32 v2, v2, v3, v4
	v_or_b32_e32 v3, 0x5a, v204
	v_cmp_lt_i32_e64 s[0:1], v18, v3
	v_or_b32_e32 v4, 0x5b, v204
	s_nop 0
	v_cndmask_b32_e64 v102, 0, v234, s[0:1]
	v_cmp_lt_i32_e64 s[0:1], v18, v4
	v_add_f32_e32 v3, v16, v102
	s_nop 0
	v_cndmask_b32_e64 v103, 0, v234, s[0:1]
	v_add_f32_e32 v4, v17, v103
	v_max3_f32 v35, v2, v3, v4
	ds_read_b128 v[2:5], v100 offset:13824
	s_waitcnt lgkmcnt(0)
	v_mfma_f32_32x32x16_bf16 v[2:17], v[2:5], v[58:61], 0
	v_mfma_f32_32x32x16_bf16 v[2:17], v[36:39], v[54:57], v[2:17]
	ds_read_b128 v[36:39], v100 offset:13888
	s_waitcnt lgkmcnt(0)
	v_mfma_f32_32x32x16_bf16 v[2:17], v[36:39], v[50:53], v[2:17]
	ds_read_b128 v[36:39], v100 offset:13920
	s_waitcnt lgkmcnt(0)
	v_mfma_f32_32x32x16_bf16 v[2:17], v[36:39], v[62:65], v[2:17]
	v_or_b32_e32 v36, 0x60, v204
	v_cmp_lt_i32_e64 s[0:1], v18, v36
	s_nop 1
	v_cndmask_b32_e64 v125, 0, v234, s[0:1]
	v_cmp_gt_i32_e64 s[0:1], v18, v36
	s_nop 5
	v_add_f32_e32 v2, v2, v125
	v_cndmask_b32_e64 v121, v234, 0, s[0:1]
	v_add_f32_e32 v3, v3, v121
	v_max3_f32 v2, v35, v2, v3
	v_or_b32_e32 v3, 0x62, v204
	v_cmp_lt_i32_e64 s[0:1], v18, v3
	s_nop 1
	v_cndmask_b32_e64 v129, 0, v234, s[0:1]
	v_add_f32_e32 v3, v4, v129
	v_or_b32_e32 v4, 0x63, v204
	v_cmp_lt_i32_e64 s[0:1], v18, v4
	s_nop 1
	v_cndmask_b32_e64 v132, 0, v234, s[0:1]
	v_add_f32_e32 v4, v5, v132
	v_max3_f32 v2, v2, v3, v4
	v_or_b32_e32 v3, 0x68, v204
	v_cmp_lt_i32_e64 s[0:1], v18, v3
	v_or_b32_e32 v4, 0x69, v204
	s_nop 0
	v_cndmask_b32_e64 v133, 0, v234, s[0:1]
	v_cmp_lt_i32_e64 s[0:1], v18, v4
	v_add_f32_e32 v3, v6, v133
	s_nop 0
	v_cndmask_b32_e64 v134, 0, v234, s[0:1]
	v_add_f32_e32 v4, v7, v134
	v_max3_f32 v2, v2, v3, v4
	v_or_b32_e32 v3, 0x6a, v204
	v_cmp_lt_i32_e64 s[0:1], v18, v3
	v_or_b32_e32 v4, 0x6b, v204
	s_nop 0
	v_cndmask_b32_e64 v135, 0, v234, s[0:1]
	v_cmp_lt_i32_e64 s[0:1], v18, v4
	v_add_f32_e32 v3, v8, v135
	s_nop 0
	v_cndmask_b32_e64 v136, 0, v234, s[0:1]
	v_add_f32_e32 v4, v9, v136
	v_max3_f32 v2, v2, v3, v4
	v_or_b32_e32 v3, 0x70, v204
	v_cmp_lt_i32_e64 s[0:1], v18, v3
	v_or_b32_e32 v4, 0x71, v204
	s_nop 0
	v_cndmask_b32_e64 v138, 0, v234, s[0:1]
	v_cmp_lt_i32_e64 s[0:1], v18, v4
	v_add_f32_e32 v3, v10, v138
	s_nop 0
	v_cndmask_b32_e64 v139, 0, v234, s[0:1]
	v_add_f32_e32 v4, v11, v139
	v_max3_f32 v2, v2, v3, v4
	v_or_b32_e32 v3, 0x72, v204
	v_cmp_lt_i32_e64 s[0:1], v18, v3
	v_or_b32_e32 v4, 0x73, v204
	s_nop 0
	v_cndmask_b32_e64 v140, 0, v234, s[0:1]
	v_cmp_lt_i32_e64 s[0:1], v18, v4
	v_add_f32_e32 v3, v12, v140
	s_nop 0
	v_cndmask_b32_e64 v141, 0, v234, s[0:1]
	v_add_f32_e32 v4, v13, v141
	v_max3_f32 v2, v2, v3, v4
	v_or_b32_e32 v3, 0x78, v204
	v_cmp_lt_i32_e64 s[0:1], v18, v3
	v_or_b32_e32 v4, 0x79, v204
	s_nop 0
	v_cndmask_b32_e64 v142, 0, v234, s[0:1]
	v_cmp_lt_i32_e64 s[0:1], v18, v4
	v_add_f32_e32 v3, v14, v142
	v_sub_u32_e32 v14, v19, v206
	v_cndmask_b32_e64 v118, 0, v234, s[0:1]
	v_add_f32_e32 v4, v15, v118
	v_max3_f32 v2, v2, v3, v4
	v_or_b32_e32 v3, 0x7a, v204
	v_cmp_lt_i32_e64 s[0:1], v18, v3
	v_or_b32_e32 v4, 0x7b, v204
	s_nop 0
	v_cndmask_b32_e64 v119, 0, v234, s[0:1]
	v_cmp_lt_i32_e64 s[0:1], v18, v4
	v_add_f32_e32 v3, v16, v119
	s_nop 0
	v_cndmask_b32_e64 v120, 0, v234, s[0:1]
	v_add_f32_e32 v4, v17, v120
	v_max3_f32 v2, v2, v3, v4
	ds_bpermute_b32 v3, v205, v2
	v_cmp_eq_u32_e64 s[0:1], s8, v1
	s_or_b64 s[0:1], vcc, s[0:1]
	s_waitcnt lgkmcnt(0)
; #define LAS __attribute__((address_space(3)))
; #define MFMA32(a, b, c) __builtin_amdgcn_mfma_f32_32x32x16_bf16((a), (b), (c), 0, 0, 0)
; __device__ __forceinline__ void nsa_unit(const Frame& F, int plane, int qt) {
;     ...
;         for (int ct = 0; ct < 4; ++ct) {
;             f32x16 sc;
; #pragma unroll
;             for (int i = 0; i < 16; ++i) sc[i] = 0.f;
; #pragma unroll
;             for (int ks = 0; ks < 4; ++ks) { const bf16x8 a = *(const LAS bf16x8*)(L + NL_KC + (32 * ct + r) * 144 + (16 * ks + 8 * h) * 2); sc = MFMA32(a, qu[ks], sc); }
; #pragma unroll
;             for (int i = 0; i < 16; ++i) { const int c = 32 * ct + (i & 3) + 8 * (i >> 2) + 4 * h; const float e = __builtin_amdgcn_exp2f(sc[i] + __int_as_float(((cmax - c) >> 31) & (int)0xF149F2CA) - mx); sc[i] = e; ls += e; }
; #pragma unroll
;             for (int q = 0; q < 4; ++q) { const float ok = __shfl_xor(sc[4 * q + 3], 32);
;                 imp[4 * ct + q] = ((sc[4 * q] + sc[4 * q + 1]) + (sc[4 * q + 2] + sc[4 * q + 3])) + (h ? ok : prev); prev = ok; }
; #pragma unroll
;             for (int s2 = 0; s2 < 2; ++s2) { const bf16x8 pf = pack_step(sc, s2);
; #pragma unroll
;                 for (int dt = 0; dt < 2; ++dt) { const LAS unsigned char* vp = L + NL_VC + (32 * dt + r) * 272 + (32 * ct + 16 * s2 + 4 * h) * 2;
;                     const s16x4 lo = *(const LAS s16x4*)vp, hi = *(const LAS s16x4*)(vp + 16);
;                     const bf16x8 vf = __builtin_shufflevector(lo, hi, 0, 1, 2, 3, 4, 5, 6, 7);
;                     outacc[dt] = MFMA32(vf, pf, outacc[dt]); } }
	v_max_f32_e32 v3, v3, v3
	v_max_f32_e32 v137, v2, v3
	v_sub_f32_e32 v2, v20, v137
	v_exp_f32_e32 v3, v2
	v_sub_f32_e32 v2, v21, v137
	v_sub_f32_e32 v10, v28, v137
	v_exp_f32_e32 v5, v2
	v_sub_f32_e32 v2, v22, v137
	v_exp_f32_e32 v37, v10
	v_sub_f32_e32 v10, v29, v137
	v_exp_f32_e32 v7, v2
	v_sub_f32_e32 v2, v23, v137
	v_exp_f32_e32 v39, v10
	v_sub_f32_e32 v10, v30, v137
	v_exp_f32_e32 v9, v2
	v_sub_f32_e32 v2, v24, v137
	v_sub_f32_e32 v4, v25, v137
	v_sub_f32_e32 v6, v26, v137
	v_sub_f32_e32 v8, v27, v137
	v_exp_f32_e32 v41, v10
	v_sub_f32_e32 v10, v31, v137
	v_exp_f32_e32 v2, v2
	v_exp_f32_e32 v4, v4
	v_exp_f32_e32 v6, v6
	v_exp_f32_e32 v8, v8
	v_exp_f32_e32 v35, v10
	v_sub_f32_e32 v10, v32, v137
	v_exp_f32_e32 v36, v10
	v_sub_f32_e32 v10, v33, v137
	v_exp_f32_e32 v38, v10
	v_sub_f32_e32 v10, v34, v137
	v_exp_f32_e32 v40, v10
	v_sub_f32_e32 v10, v42, v137
	v_exp_f32_e32 v34, v10
	v_add_f32_e32 v10, v2, v4
	v_add_f32_e32 v11, v3, v5
	v_add_f32_e32 v12, v6, v8
	v_add_f32_e32 v13, v7, v9
	ds_bpermute_b32 v45, v205, v9
	v_add_f32_e32 v42, v10, v12
	v_add_f32_e32 v43, v11, v13
	v_add_f32_e32 v10, 0, v3
	ds_bpermute_b32 v151, v205, v8
	v_add_f32_e32 v10, v5, v10
	v_add_f32_e32 v10, v7, v10
	v_add_f32_e32 v10, v9, v10
	v_add_f32_e32 v10, v2, v10
	v_mad_u32_u24 v22, v83, s11, v14
	v_add_f32_e32 v10, v4, v10
	v_add_u32_e32 v145, 0x4800, v22
	v_add_f32_e32 v10, v6, v10
	v_cvt_pk_bf16_f32 v18, v3, v5
	v_cvt_pk_bf16_f32 v19, v7, v9
	v_cvt_pk_bf16_f32 v20, v2, v4
	v_cvt_pk_bf16_f32 v21, v6, v8
	s_nop 1
	ds_read2_b64 v[2:5], v145 offset1:2
	s_waitcnt lgkmcnt(1)
	v_cndmask_b32_e32 v44, v151, v45, vcc
	v_cndmask_b32_e64 v45, v45, 0, vcc
	v_add_f32_e32 v46, v8, v10
	v_add_f32_e32 v80, v44, v42
	v_add_f32_e32 v81, v45, v43
	v_add_f32_e32 v42, v36, v38
	v_add_f32_e32 v43, v37, v39
	v_add_f32_e32 v44, v40, v34
	v_add_f32_e32 v45, v41, v35
	v_add_u32_e32 v146, 0x6800, v22
	v_add_f32_e32 v84, v42, v44
	v_add_f32_e32 v85, v43, v45
	v_add_f32_e32 v42, v37, v46
	v_add_f32_e32 v42, v39, v42
	v_add_f32_e32 v42, v41, v42
	v_add_f32_e32 v42, v35, v42
	v_add_f32_e32 v42, v36, v42
	v_add_f32_e32 v42, v38, v42
	ds_read2_b64 v[22:25], v146 offset0:64 offset1:66
	v_add_f32_e32 v46, v40, v42
	v_cvt_pk_bf16_f32 v42, v37, v39
	v_cvt_pk_bf16_f32 v43, v41, v35
	v_cvt_pk_bf16_f32 v44, v36, v38
	v_cvt_pk_bf16_f32 v45, v40, v34
	s_nop 1
	ds_read2_b64 v[36:39], v145 offset0:4 offset1:6
	s_waitcnt lgkmcnt(2)
	v_mfma_f32_32x32x16_bf16 v[2:17], v[2:5], v[18:21], 0
	ds_bpermute_b32 v153, v205, v35
	ds_bpermute_b32 v152, v205, v34
	v_add_f32_e32 v158, v34, v46
	s_waitcnt lgkmcnt(2)
	v_mfma_f32_32x32x16_bf16 v[2:17], v[36:39], v[42:45], v[2:17]
	ds_read2_b64 v[36:39], v146 offset0:68 offset1:70
	v_mfma_f32_32x32x16_bf16 v[18:33], v[22:25], v[18:21], 0
	s_waitcnt lgkmcnt(0)
	v_mfma_f32_32x32x16_bf16 v[18:33], v[36:39], v[42:45], v[18:33]
	ds_read_b128 v[34:37], v100 offset:4608
	ds_read_b128 v[154:157], v100 offset:4640
	s_waitcnt lgkmcnt(1)
	v_mfma_f32_32x32x16_bf16 v[34:49], v[34:37], v[58:61], 0
	s_waitcnt lgkmcnt(0)
	v_mfma_f32_32x32x16_bf16 v[34:49], v[154:157], v[54:57], v[34:49]
	ds_read_b128 v[154:157], v100 offset:4672
	s_waitcnt lgkmcnt(0)
	v_mfma_f32_32x32x16_bf16 v[34:49], v[154:157], v[50:53], v[34:49]
	ds_read_b128 v[154:157], v100 offset:4704
	s_waitcnt lgkmcnt(0)
	v_mfma_f32_32x32x16_bf16 v[34:49], v[154:157], v[62:65], v[34:49]
	s_nop 11
	v_add_f32_e32 v34, v34, v82
	v_sub_f32_e32 v34, v34, v137
	v_exp_f32_e32 v87, v34
	v_add_f32_e32 v34, v35, v79
	v_sub_f32_e32 v34, v34, v137
	v_exp_f32_e32 v91, v34
	v_add_f32_e32 v34, v36, v93
	v_sub_f32_e32 v34, v34, v137
	v_exp_f32_e32 v93, v34
	v_add_f32_e32 v34, v37, v95
	v_sub_f32_e32 v34, v34, v137
	v_exp_f32_e32 v95, v34
	v_add_f32_e32 v34, v38, v86
	v_sub_f32_e32 v34, v34, v137
	v_exp_f32_e32 v86, v34
	v_add_f32_e32 v34, v39, v90
	v_sub_f32_e32 v34, v34, v137
	v_exp_f32_e32 v90, v34
	v_add_f32_e32 v34, v40, v92
	v_sub_f32_e32 v34, v34, v137
	v_exp_f32_e32 v92, v34
	v_add_f32_e32 v34, v41, v94
	v_sub_f32_e32 v34, v34, v137
	v_exp_f32_e32 v94, v34
	v_add_f32_e32 v34, v42, v150
	v_sub_f32_e32 v34, v34, v137
	v_exp_f32_e32 v35, v34
	v_add_f32_e32 v34, v43, v149
	v_sub_f32_e32 v34, v34, v137
	v_exp_f32_e32 v37, v34
	v_add_f32_e32 v34, v44, v148
	v_sub_f32_e32 v34, v34, v137
	v_exp_f32_e32 v39, v34
	v_add_f32_e32 v34, v45, v147
	v_sub_f32_e32 v34, v34, v137
	v_exp_f32_e32 v41, v34
	v_add_f32_e32 v34, v46, v88
	v_add_f32_e32 v36, v47, v89
	v_add_f32_e32 v38, v48, v143
	v_add_f32_e32 v40, v49, v144
	v_sub_f32_e32 v34, v34, v137
	v_sub_f32_e32 v36, v36, v137
	v_sub_f32_e32 v38, v38, v137
	v_sub_f32_e32 v40, v40, v137
	v_exp_f32_e32 v34, v34
	v_exp_f32_e32 v36, v36
	v_exp_f32_e32 v38, v38
	v_exp_f32_e32 v40, v40
	ds_bpermute_b32 v143, v205, v95
	v_add_f32_e32 v42, v34, v36
	v_add_f32_e32 v43, v35, v37
	ds_bpermute_b32 v144, v205, v94
	v_add_f32_e32 v44, v38, v40
	v_add_f32_e32 v45, v39, v41
	v_or_b32_e32 v79, 4, v1
	v_add_f32_e32 v88, v42, v44
	v_add_f32_e32 v89, v43, v45
	v_cndmask_b32_e32 v43, v153, v151, vcc
	v_cndmask_b32_e32 v42, v152, v153, vcc
	v_add_f32_e32 v84, v84, v42
	v_add_f32_e32 v85, v85, v43
	v_add_f32_e32 v42, v86, v90
	v_add_f32_e32 v43, v87, v91
	v_add_f32_e32 v44, v92, v94
	v_add_f32_e32 v45, v93, v95
	v_or_b32_e32 v82, 6, v1
	v_add_f32_e32 v148, v42, v44
	v_add_f32_e32 v149, v43, v45
	v_add_f32_e32 v42, v87, v158
	v_add_f32_e32 v42, v91, v42
	v_add_f32_e32 v42, v93, v42
	v_add_f32_e32 v42, v95, v42
	v_add_f32_e32 v42, v86, v42
	v_add_f32_e32 v42, v90, v42
	v_add_f32_e32 v42, v92, v42
	v_add_f32_e32 v147, v94, v42
	v_cvt_pk_bf16_f32 v42, v87, v91
	v_cvt_pk_bf16_f32 v43, v93, v95
	v_cvt_pk_bf16_f32 v44, v86, v90
	v_cvt_pk_bf16_f32 v45, v92, v94
	s_nop 1
	ds_read2_b64 v[46:49], v145 offset0:8 offset1:10
	s_waitcnt lgkmcnt(0)
; #define LAS __attribute__((address_space(3)))
; #define MFMA32(a, b, c) __builtin_amdgcn_mfma_f32_32x32x16_bf16((a), (b), (c), 0, 0, 0)
; __device__ __forceinline__ void nsa_unit(const Frame& F, int plane, int qt) {
;     ...
;         for (int ct = 0; ct < 4; ++ct) {
;             f32x16 sc;
; #pragma unroll
;             for (int i = 0; i < 16; ++i) sc[i] = 0.f;
; #pragma unroll
;             for (int ks = 0; ks < 4; ++ks) { const bf16x8 a = *(const LAS bf16x8*)(L + NL_KC + (32 * ct + r) * 144 + (16 * ks + 8 * h) * 2); sc = MFMA32(a, qu[ks], sc); }
; #pragma unroll
;             for (int i = 0; i < 16; ++i) { const int c = 32 * ct + (i & 3) + 8 * (i >> 2) + 4 * h; const float e = __builtin_amdgcn_exp2f(sc[i] + __int_as_float(((cmax - c) >> 31) & (int)0xF149F2CA) - mx); sc[i] = e; ls += e; }
; #pragma unroll
;             for (int q = 0; q < 4; ++q) { const float ok = __shfl_xor(sc[4 * q + 3], 32);
;                 imp[4 * ct + q] = ((sc[4 * q] + sc[4 * q + 1]) + (sc[4 * q + 2] + sc[4 * q + 3])) + (h ? ok : prev); prev = ok; }
; #pragma unroll
;             for (int s2 = 0; s2 < 2; ++s2) { const bf16x8 pf = pack_step(sc, s2);
; #pragma unroll
;                 for (int dt = 0; dt < 2; ++dt) { const LAS unsigned char* vp = L + NL_VC + (32 * dt + r) * 272 + (32 * ct + 16 * s2 + 4 * h) * 2;
;                     const s16x4 lo = *(const LAS s16x4*)vp, hi = *(const LAS s16x4*)(vp + 16);
;                     const bf16x8 vf = __builtin_shufflevector(lo, hi, 0, 1, 2, 3, 4, 5, 6, 7);
;                     outacc[dt] = MFMA32(vf, pf, outacc[dt]); } }
	v_mfma_f32_32x32x16_bf16 v[2:17], v[46:49], v[42:45], v[2:17]
	ds_read2_b64 v[46:49], v146 offset0:72 offset1:74
	ds_bpermute_b32 v150, v205, v41
	s_waitcnt lgkmcnt(1)
	v_mfma_f32_32x32x16_bf16 v[18:33], v[46:49], v[42:45], v[18:33]
	v_cndmask_b32_e32 v43, v143, v152, vcc
	v_cndmask_b32_e32 v42, v144, v143, vcc
	v_add_f32_e64 v86, v148, v42
	v_add_f32_e64 v87, v149, v43
	v_add_f32_e32 v42, v35, v147
	v_add_f32_e32 v42, v37, v42
	v_add_f32_e32 v42, v39, v42
	v_add_f32_e32 v42, v41, v42
	v_add_f32_e32 v42, v34, v42
	v_add_f32_e32 v42, v36, v42
	v_add_f32_e32 v46, v38, v42
	v_cvt_pk_bf16_f32 v42, v35, v37
	v_cvt_pk_bf16_f32 v43, v39, v41
	v_cvt_pk_bf16_f32 v44, v34, v36
	v_cvt_pk_bf16_f32 v45, v38, v40
	s_nop 1
	ds_read2_b64 v[34:37], v145 offset0:12 offset1:14
	s_waitcnt lgkmcnt(0)
	v_mfma_f32_32x32x16_bf16 v[2:17], v[34:37], v[42:45], v[2:17]
	ds_read2_b64 v[34:37], v146 offset0:76 offset1:78
	ds_bpermute_b32 v143, v205, v40
	v_add_f32_e32 v147, v40, v46
	s_waitcnt lgkmcnt(1)
	v_mfma_f32_32x32x16_bf16 v[18:33], v[34:37], v[42:45], v[18:33]
	ds_read_b128 v[34:37], v100 offset:9216
	ds_read_b128 v[90:93], v100 offset:9248
	s_waitcnt lgkmcnt(1)
	v_mfma_f32_32x32x16_bf16 v[34:49], v[34:37], v[58:61], 0
	s_waitcnt lgkmcnt(0)
	v_mfma_f32_32x32x16_bf16 v[34:49], v[90:93], v[54:57], v[34:49]
	ds_read_b128 v[90:93], v100 offset:9280
	s_waitcnt lgkmcnt(0)
	v_mfma_f32_32x32x16_bf16 v[34:49], v[90:93], v[50:53], v[34:49]
	ds_read_b128 v[90:93], v100 offset:9312
	s_waitcnt lgkmcnt(0)
	v_mfma_f32_32x32x16_bf16 v[34:49], v[90:93], v[62:65], v[34:49]
	s_nop 11
	v_add_f32_e32 v34, v34, v105
	v_sub_f32_e32 v34, v34, v137
	v_exp_f32_e32 v91, v34
	v_add_f32_e32 v34, v47, v101
	v_sub_f32_e32 v34, v34, v137
	v_add_f32_e32 v40, v40, v110
	v_exp_f32_e32 v110, v34
	v_add_f32_e32 v34, v48, v102
	v_sub_f32_e32 v34, v34, v137
	v_add_f32_e32 v42, v42, v112
	v_add_f32_e32 v43, v43, v113
	v_add_f32_e32 v44, v44, v115
	v_add_f32_e32 v45, v45, v116
	v_add_f32_e32 v46, v46, v117
	v_exp_f32_e32 v112, v34
	v_add_f32_e32 v34, v49, v103
	v_sub_f32_e32 v42, v42, v137
	v_sub_f32_e32 v43, v43, v137
	v_sub_f32_e32 v44, v44, v137
	v_sub_f32_e32 v45, v45, v137
	v_sub_f32_e32 v46, v46, v137
	v_sub_f32_e32 v34, v34, v137
	v_add_f32_e32 v38, v38, v108
	v_add_f32_e32 v39, v39, v109
	v_add_f32_e32 v41, v41, v111
	v_exp_f32_e32 v109, v42
	v_exp_f32_e32 v111, v43
	v_exp_f32_e32 v113, v44
	v_exp_f32_e32 v117, v45
	v_exp_f32_e32 v108, v46
	v_exp_f32_e32 v116, v34
	v_add_f32_e32 v35, v35, v104
	v_add_f32_e32 v36, v36, v106
	v_add_f32_e32 v37, v37, v107
	v_sub_f32_e32 v35, v35, v137
	v_sub_f32_e32 v36, v36, v137
	v_sub_f32_e32 v37, v37, v137
	v_sub_f32_e32 v38, v38, v137
	v_sub_f32_e32 v39, v39, v137
	v_sub_f32_e32 v40, v40, v137
	v_sub_f32_e32 v34, v41, v137
	v_exp_f32_e32 v95, v35
	v_exp_f32_e32 v105, v36
	v_exp_f32_e32 v107, v37
	v_exp_f32_e32 v90, v38
	v_exp_f32_e32 v94, v39
	v_exp_f32_e32 v104, v40
	v_exp_f32_e32 v106, v34
	v_add_f32_e32 v34, v108, v110
	v_add_f32_e32 v35, v109, v111
	v_add_f32_e32 v36, v112, v116
	v_add_f32_e32 v37, v113, v117
	v_cndmask_b32_e32 v43, v150, v144, vcc
	v_add_f32_e32 v92, v34, v36
	v_add_f32_e32 v93, v35, v37
	v_cvt_pk_bf16_f32 v34, v91, v95
	v_cvt_pk_bf16_f32 v35, v105, v107
	v_cvt_pk_bf16_f32 v36, v90, v94
	v_cvt_pk_bf16_f32 v37, v104, v106
	s_nop 1
	ds_read2_b64 v[38:41], v145 offset0:16 offset1:18
	v_cndmask_b32_e32 v42, v143, v150, vcc
	v_add_f32_e32 v88, v88, v42
	v_add_f32_e32 v89, v89, v43
	v_add_f32_e32 v42, v90, v94
	v_add_f32_e32 v43, v91, v95
	v_add_f32_e32 v44, v104, v106
	v_add_f32_e32 v45, v105, v107
	ds_bpermute_b32 v101, v205, v107
	v_add_f32_e32 v102, v42, v44
	v_add_f32_e32 v103, v43, v45
	v_add_f32_e32 v42, v91, v147
	v_add_f32_e32 v46, v95, v42
	ds_read2_b64 v[42:45], v146 offset0:80 offset1:82
	ds_bpermute_b32 v115, v205, v106
	s_waitcnt lgkmcnt(3)
	v_mfma_f32_32x32x16_bf16 v[2:17], v[38:41], v[34:37], v[2:17]
	v_add_f32_e32 v38, v105, v46
	v_add_f32_e32 v38, v107, v38
	v_add_f32_e32 v38, v90, v38
	v_add_f32_e32 v38, v94, v38
	v_add_f32_e32 v90, v104, v38
	v_cvt_pk_bf16_f32 v38, v109, v111
	v_cvt_pk_bf16_f32 v39, v113, v117
	v_cvt_pk_bf16_f32 v40, v108, v110
	v_cvt_pk_bf16_f32 v41, v112, v116
	s_nop 1
	ds_read2_b64 v[46:49], v145 offset0:20 offset1:22
	s_waitcnt lgkmcnt(2)
	v_mfma_f32_32x32x16_bf16 v[18:33], v[42:45], v[34:37], v[18:33]
	v_cndmask_b32_e32 v35, v101, v143, vcc
	s_waitcnt lgkmcnt(1)
	v_cndmask_b32_e32 v34, v115, v101, vcc
	v_add_f32_e32 v42, v106, v90
	v_add_f32_e64 v90, v102, v34
	v_add_f32_e64 v91, v103, v35
	ds_read2_b64 v[34:37], v146 offset0:84 offset1:86
	v_add_f32_e32 v42, v109, v42
	v_add_f32_e32 v42, v111, v42
	s_waitcnt lgkmcnt(1)
	v_mfma_f32_32x32x16_bf16 v[2:17], v[46:49], v[38:41], v[2:17]
	v_add_f32_e32 v42, v113, v42
	v_add_f32_e32 v42, v117, v42
	v_add_f32_e32 v42, v108, v42
	v_add_f32_e32 v42, v110, v42
	v_add_f32_e32 v42, v112, v42
	ds_bpermute_b32 v94, v205, v117
	ds_bpermute_b32 v95, v205, v116
	s_waitcnt lgkmcnt(2)
	v_mfma_f32_32x32x16_bf16 v[18:33], v[34:37], v[38:41], v[18:33]
	v_add_f32_e32 v101, v116, v42
	ds_read_b128 v[34:37], v100 offset:13824
	s_waitcnt lgkmcnt(0)
	v_mfma_f32_32x32x16_bf16 v[34:49], v[34:37], v[58:61], 0
	ds_read_b128 v[58:61], v100 offset:13856
	s_waitcnt lgkmcnt(0)
	v_mfma_f32_32x32x16_bf16 v[34:49], v[58:61], v[54:57], v[34:49]
	ds_read_b128 v[54:57], v100 offset:13888
	s_waitcnt lgkmcnt(0)
	v_mfma_f32_32x32x16_bf16 v[34:49], v[54:57], v[50:53], v[34:49]
	ds_read_b128 v[50:53], v100 offset:13920
	s_waitcnt lgkmcnt(0)
; #define LAS __attribute__((address_space(3)))
; #define MFMA32(a, b, c) __builtin_amdgcn_mfma_f32_32x32x16_bf16((a), (b), (c), 0, 0, 0)
; __device__ __forceinline__ void nsa_unit(const Frame& F, int plane, int qt) {
;     ...
;             for (int ks = 0; ks < 4; ++ks) { const bf16x8 a = *(const LAS bf16x8*)(L + NL_KC + (32 * ct + r) * 144 + (16 * ks + 8 * h) * 2); sc = MFMA32(a, qu[ks], sc); }
; #pragma unroll
;             for (int i = 0; i < 16; ++i) { const int c = 32 * ct + (i & 3) + 8 * (i >> 2) + 4 * h; const float e = __builtin_amdgcn_exp2f(sc[i] + __int_as_float(((cmax - c) >> 31) & (int)0xF149F2CA) - mx); sc[i] = e; ls += e; }
; #pragma unroll
;             for (int q = 0; q < 4; ++q) { const float ok = __shfl_xor(sc[4 * q + 3], 32);
;                 imp[4 * ct + q] = ((sc[4 * q] + sc[4 * q + 1]) + (sc[4 * q + 2] + sc[4 * q + 3])) + (h ? ok : prev); prev = ok; }
; #pragma unroll
;             for (int s2 = 0; s2 < 2; ++s2) { const bf16x8 pf = pack_step(sc, s2);
; #pragma unroll
;                 for (int dt = 0; dt < 2; ++dt) { const LAS unsigned char* vp = L + NL_VC + (32 * dt + r) * 272 + (32 * ct + 16 * s2 + 4 * h) * 2;
;                     const s16x4 lo = *(const LAS s16x4*)vp, hi = *(const LAS s16x4*)(vp + 16);
;                     const bf16x8 vf = __builtin_shufflevector(lo, hi, 0, 1, 2, 3, 4, 5, 6, 7);
;                     outacc[dt] = MFMA32(vf, pf, outacc[dt]); } }
;             __builtin_amdgcn_sched_barrier(0);
;         }
;         ls += __shfl_xor(ls, 32);
;         const float inv = ls > 0.f ? 1.f / ls : 0.f;
; #pragma unroll
;         for (int k = 0; k < 16; ++k) imp[k] *= inv;
;         { LAS float* ob = (LAS float*)(L + NL_OUT + w * 8192) + lane; const float og = inv * gate_c;
; #pragma unroll
;           for (int i = 0; i < 16; ++i) { ob[i * 64] = outacc[0][i] * og; ob[(16 + i) * 64] = outacc[1][i] * og; } }
; #pragma unroll
;         for (int k = 0; k < 16; ++k) { imp[k] += __shfl_xor(imp[k], 1); imp[k] += __shfl_xor(imp[k], 2);
	v_mfma_f32_32x32x16_bf16 v[34:49], v[50:53], v[62:65], v[34:49]
	s_nop 11
	v_add_f32_e32 v34, v34, v125
	v_sub_f32_e32 v34, v34, v137
	v_exp_f32_e32 v51, v34
	v_add_f32_e32 v34, v47, v118
	v_sub_f32_e32 v34, v34, v137
	v_exp_f32_e32 v60, v34
	v_add_f32_e32 v34, v48, v119
	v_sub_f32_e32 v34, v34, v137
	v_add_f32_e32 v42, v42, v138
	v_add_f32_e32 v43, v43, v139
	v_add_f32_e32 v44, v44, v140
	v_add_f32_e32 v45, v45, v141
	v_add_f32_e32 v46, v46, v142
	v_exp_f32_e32 v62, v34
	v_add_f32_e32 v34, v49, v120
	v_sub_f32_e32 v42, v42, v137
	v_sub_f32_e32 v43, v43, v137
	v_sub_f32_e32 v44, v44, v137
	v_sub_f32_e32 v45, v45, v137
	v_sub_f32_e32 v46, v46, v137
	v_sub_f32_e32 v34, v34, v137
	v_exp_f32_e32 v59, v42
	v_exp_f32_e32 v61, v43
	v_exp_f32_e32 v63, v44
	v_exp_f32_e32 v65, v45
	v_exp_f32_e32 v58, v46
	v_exp_f32_e32 v64, v34
	v_add_f32_e32 v35, v35, v121
	v_add_f32_e32 v36, v36, v129
	v_add_f32_e32 v37, v37, v132
	v_add_f32_e32 v41, v41, v136
	v_add_f32_e32 v38, v38, v133
	v_add_f32_e32 v39, v39, v134
	v_add_f32_e32 v40, v40, v135
	v_sub_f32_e32 v35, v35, v137
	v_sub_f32_e32 v36, v36, v137
	v_sub_f32_e32 v37, v37, v137
	v_sub_f32_e32 v34, v41, v137
	v_sub_f32_e32 v38, v38, v137
	v_sub_f32_e32 v39, v39, v137
	v_sub_f32_e32 v40, v40, v137
	v_exp_f32_e32 v53, v35
	v_exp_f32_e32 v55, v36
	v_exp_f32_e32 v57, v37
	v_exp_f32_e32 v56, v34
	v_add_f32_e32 v34, v58, v60
	v_add_f32_e32 v35, v59, v61
	v_add_f32_e32 v36, v62, v64
	v_add_f32_e32 v37, v63, v65
	v_exp_f32_e32 v50, v38
	v_exp_f32_e32 v52, v39
	v_exp_f32_e32 v54, v40
	v_add_f32_e32 v48, v34, v36
	v_add_f32_e32 v49, v35, v37
	v_cvt_pk_bf16_f32 v36, v51, v53
	v_cvt_pk_bf16_f32 v37, v55, v57
	v_cvt_pk_bf16_f32 v38, v50, v52
	v_cvt_pk_bf16_f32 v39, v54, v56
	s_nop 1
	ds_read2_b64 v[40:43], v145 offset0:24 offset1:26
	v_cndmask_b32_e32 v35, v94, v115, vcc
	v_cndmask_b32_e32 v34, v95, v94, vcc
	v_add_f32_e32 v44, v50, v52
	v_add_f32_e32 v45, v51, v53
	v_add_f32_e32 v46, v54, v56
	v_add_f32_e32 v47, v55, v57
	v_add_f32_e32 v34, v92, v34
	v_add_f32_e32 v35, v93, v35
	v_add_f32_e32 v92, v44, v46
	v_add_f32_e32 v93, v45, v47
	ds_read2_b64 v[44:47], v146 offset0:88 offset1:90
	v_add_f32_e32 v51, v51, v101
	s_waitcnt lgkmcnt(1)
	v_mfma_f32_32x32x16_bf16 v[2:17], v[40:43], v[36:39], v[2:17]
	v_add_f32_e32 v40, v53, v51
	v_add_f32_e32 v40, v55, v40
	ds_bpermute_b32 v100, v205, v57
	ds_bpermute_b32 v94, v205, v56
	v_add_f32_e32 v40, v57, v40
	v_add_f32_e32 v40, v50, v40
	ds_bpermute_b32 v50, v205, v65
	ds_bpermute_b32 v51, v205, v64
	v_add_f32_e32 v40, v52, v40
	s_waitcnt lgkmcnt(4)
	v_mfma_f32_32x32x16_bf16 v[18:33], v[44:47], v[36:39], v[18:33]
	s_waitcnt lgkmcnt(3)
	v_cndmask_b32_e32 v37, v100, v95, vcc
	s_waitcnt lgkmcnt(2)
	v_cndmask_b32_e32 v36, v94, v100, vcc
	v_add_f32_e32 v40, v54, v40
	v_add_f32_e32 v38, v92, v36
	v_add_f32_e32 v39, v93, v37
	s_waitcnt lgkmcnt(1)
	v_cndmask_b32_e32 v37, v50, v94, vcc
	s_waitcnt lgkmcnt(0)
	v_cndmask_b32_e32 v36, v51, v50, vcc
	v_add_f32_e32 v52, v56, v40
	v_cvt_pk_bf16_f32 v40, v59, v61
	v_cvt_pk_bf16_f32 v41, v63, v65
	v_cvt_pk_bf16_f32 v42, v58, v60
	v_cvt_pk_bf16_f32 v43, v62, v64
	s_nop 1
	ds_read2_b64 v[44:47], v145 offset0:28 offset1:30
	v_add_f32_e32 v36, v48, v36
	v_add_f32_e32 v37, v49, v37
	ds_read2_b64 v[48:51], v146 offset0:92 offset1:94
	s_waitcnt lgkmcnt(1)
	v_mfma_f32_32x32x16_bf16 v[2:17], v[44:47], v[40:43], v[2:17]
	v_add_f32_e32 v44, v59, v52
	v_add_f32_e32 v44, v61, v44
	v_add_f32_e32 v44, v63, v44
	v_add_f32_e32 v44, v65, v44
	v_add_f32_e32 v44, v58, v44
	v_add_f32_e32 v44, v60, v44
	v_add_f32_e32 v44, v62, v44
	s_waitcnt lgkmcnt(0)
	v_mfma_f32_32x32x16_bf16 v[18:33], v[48:51], v[40:43], v[18:33]
	v_add_f32_e32 v40, v64, v44
	ds_bpermute_b32 v41, v205, v40
	v_mov_b32_e32 v217, 0
	s_waitcnt lgkmcnt(0)
	v_add_f32_e32 v40, v40, v41
	v_div_scale_f32 v41, s[10:11], v40, v40, 1.0
	v_rcp_f32_e32 v42, v41
	v_div_scale_f32 v43, vcc, 1.0, v40, 1.0
	v_fma_f32 v44, -v41, v42, 1.0
	v_fmac_f32_e32 v42, v44, v42
	v_mul_f32_e32 v44, v43, v42
	v_fma_f32 v45, -v41, v44, v43
	v_fmac_f32_e32 v44, v45, v42
	v_fma_f32 v41, -v41, v44, v43
	v_div_fmas_f32 v41, v41, v42, v44
	v_div_fixup_f32 v41, v41, v40, 1.0
	v_cmp_lt_f32_e32 vcc, 0, v40
	s_nop 1
	v_cndmask_b32_e32 v40, 0, v41, vcc
	v_mul_f32_e32 v42, v80, v40
	v_mul_f32_e32 v43, v81, v40
	v_mul_f32_e32 v44, v84, v40
	v_mul_f32_e32 v45, v85, v40
	v_mul_f32_e32 v46, v86, v40
	v_mul_f32_e32 v47, v87, v40
	v_mul_f32_e32 v48, v88, v40
	v_mul_f32_e32 v49, v89, v40
	v_mul_f32_e32 v50, v90, v40
	v_mul_f32_e32 v51, v91, v40
	v_mul_f32_e32 v52, v34, v40
	v_mul_f32_e32 v53, v35, v40
	v_mul_f32_e32 v54, v38, v40
	v_mul_f32_e32 v55, v39, v40
	v_mul_f32_e32 v56, v36, v40
	v_mul_f32_e32 v57, v37, v40
	v_mul_f32_e32 v41, v122, v40
	v_mul_f32_e32 v2, v2, v41
	v_mul_f32_e32 v3, v3, v41
	v_mul_f32_e32 v18, v18, v41
	ds_write2st64_b32 v203, v2, v3 offset0:212 offset1:213
	v_mul_f32_e32 v2, v19, v41
	ds_write2st64_b32 v203, v18, v2 offset0:228 offset1:229
	v_mul_f32_e32 v2, v4, v41
	v_mul_f32_e32 v4, v5, v41
	v_mul_f32_e32 v3, v20, v41
	ds_write2st64_b32 v203, v2, v4 offset0:214 offset1:215
	v_mul_f32_e32 v2, v21, v41
	ds_write2st64_b32 v203, v3, v2 offset0:230 offset1:231
	v_mul_f32_e32 v2, v6, v41
	v_mul_f32_e32 v4, v7, v41
	v_mul_f32_e32 v3, v22, v41
	ds_write2st64_b32 v203, v2, v4 offset0:216 offset1:217
	v_mul_f32_e32 v2, v23, v41
	ds_write2st64_b32 v203, v3, v2 offset0:232 offset1:233
	v_mul_f32_e32 v2, v8, v41
	v_mul_f32_e32 v4, v9, v41
	v_mul_f32_e32 v3, v24, v41
	ds_write2st64_b32 v203, v2, v4 offset0:218 offset1:219
	v_mul_f32_e32 v2, v25, v41
	ds_write2st64_b32 v203, v3, v2 offset0:234 offset1:235
	v_mul_f32_e32 v2, v10, v41
	v_mul_f32_e32 v4, v11, v41
	v_mul_f32_e32 v3, v26, v41
	ds_write2st64_b32 v203, v2, v4 offset0:220 offset1:221
	v_mul_f32_e32 v2, v27, v41
	ds_write2st64_b32 v203, v3, v2 offset0:236 offset1:237
	v_mul_f32_e32 v2, v12, v41
	v_mul_f32_e32 v4, v13, v41
	v_mul_f32_e32 v3, v28, v41
	ds_write2st64_b32 v203, v2, v4 offset0:222 offset1:223
	v_mul_f32_e32 v2, v29, v41
	ds_write2st64_b32 v203, v3, v2 offset0:238 offset1:239
	v_mul_f32_e32 v2, v14, v41
	v_mul_f32_e32 v4, v15, v41
	v_mul_f32_e32 v3, v30, v41
	ds_write2st64_b32 v203, v2, v4 offset0:224 offset1:225
	v_mul_f32_e32 v2, v31, v41
	ds_write2st64_b32 v203, v3, v2 offset0:240 offset1:241
	ds_bpermute_b32 v3, v99, v43
	ds_bpermute_b32 v2, v99, v42
	v_mul_f32_e32 v4, v16, v41
	v_mul_f32_e32 v5, v17, v41
	ds_write2st64_b32 v203, v4, v5 offset0:226 offset1:227
	ds_bpermute_b32 v7, v99, v45
	s_waitcnt lgkmcnt(2)
; #define LAS __attribute__((address_space(3)))
; __device__ __forceinline__ void nsa_unit(const Frame& F, int plane, int qt) {
;     ...
;         for (int k = 0; k < 16; ++k) imp[k] *= inv;
;         { LAS float* ob = (LAS float*)(L + NL_OUT + w * 8192) + lane; const float og = inv * gate_c;
; #pragma unroll
;           for (int i = 0; i < 16; ++i) { ob[i * 64] = outacc[0][i] * og; ob[(16 + i) * 64] = outacc[1][i] * og; } }
; #pragma unroll
;         for (int k = 0; k < 16; ++k) { imp[k] += __shfl_xor(imp[k], 1); imp[k] += __shfl_xor(imp[k], 2);
;             const int jb = 2 * k + h; imp[k] = (jb == 0 || jb == cur) ? 1e9f : (jb <= cur ? imp[k] : -1e9f); }
	v_fma_f32 v2, v80, v40, v2
	v_fma_f32 v3, v81, v40, v3
	ds_bpermute_b32 v5, v98, v3
	ds_bpermute_b32 v4, v98, v2
	ds_bpermute_b32 v6, v99, v44
	v_mul_f32_e32 v8, v32, v41
	v_mul_f32_e32 v9, v33, v41
	ds_write2st64_b32 v203, v8, v9 offset0:242 offset1:243
	s_waitcnt lgkmcnt(2)
	v_add_f32_e32 v2, v2, v4
	v_add_f32_e32 v3, v3, v5
	s_waitcnt lgkmcnt(1)
	v_fma_f32 v4, v84, v40, v6
	v_fma_f32 v5, v85, v40, v7
	ds_bpermute_b32 v7, v98, v5
	ds_bpermute_b32 v6, v98, v4
	v_cmp_ge_u32_e32 vcc, s8, v68
	s_waitcnt lgkmcnt(0)
	v_add_f32_e32 v4, v4, v6
	v_add_f32_e32 v5, v5, v7
	ds_bpermute_b32 v7, v99, v47
	ds_bpermute_b32 v6, v99, v46
	v_cndmask_b32_e32 v2, v235, v2, vcc
	v_cmp_ge_u32_e32 vcc, s8, v1
	s_waitcnt lgkmcnt(0)
	v_fma_f32 v6, v86, v40, v6
	v_fma_f32 v7, v87, v40, v7
	ds_bpermute_b32 v9, v98, v7
	ds_bpermute_b32 v8, v98, v6
	v_cndmask_b32_e32 v3, v235, v3, vcc
	v_cmp_ne_u32_e32 vcc, s8, v68
	v_cndmask_b32_e64 v3, v3, v236, s[0:1]
	s_waitcnt lgkmcnt(0)
	v_add_f32_e32 v6, v6, v8
	v_add_f32_e32 v7, v7, v9
	ds_bpermute_b32 v9, v99, v49
	ds_bpermute_b32 v8, v99, v48
	v_cndmask_b32_e32 v2, v236, v2, vcc
	v_cmp_ge_u32_e32 vcc, s8, v82
	s_waitcnt lgkmcnt(0)
	v_fma_f32 v8, v88, v40, v8
	v_fma_f32 v9, v89, v40, v9
	ds_bpermute_b32 v11, v98, v9
	ds_bpermute_b32 v10, v98, v8
	v_cndmask_b32_e32 v4, v235, v4, vcc
	v_cmp_ge_u32_e32 vcc, s8, v79
	s_waitcnt lgkmcnt(0)
	v_add_f32_e32 v8, v8, v10
	v_add_f32_e32 v9, v9, v11
	ds_bpermute_b32 v11, v99, v51
	ds_bpermute_b32 v10, v99, v50
	v_cndmask_b32_e32 v5, v235, v5, vcc
	v_cmp_ne_u32_e32 vcc, s8, v79
	s_waitcnt lgkmcnt(0)
	v_fma_f32 v10, v90, v40, v10
	v_fma_f32 v11, v91, v40, v11
	ds_bpermute_b32 v13, v98, v11
	ds_bpermute_b32 v12, v98, v10
	v_cndmask_b32_e32 v5, v236, v5, vcc
	v_cmp_ne_u32_e32 vcc, s8, v82
	s_waitcnt lgkmcnt(0)
	v_add_f32_e32 v10, v10, v12
	v_add_f32_e32 v11, v11, v13
	ds_bpermute_b32 v13, v99, v53
	ds_bpermute_b32 v12, v99, v52
	v_cndmask_b32_e32 v4, v236, v4, vcc
	v_cmp_ge_u32_e32 vcc, s8, v78
	s_waitcnt lgkmcnt(0)
	v_fma_f32 v12, v34, v40, v12
	v_fma_f32 v13, v35, v40, v13
	ds_bpermute_b32 v15, v98, v13
	ds_bpermute_b32 v14, v98, v12
	v_cndmask_b32_e32 v6, v235, v6, vcc
	v_cmp_ge_u32_e32 vcc, s8, v77
	s_waitcnt lgkmcnt(0)
	v_add_f32_e32 v12, v12, v14
	v_add_f32_e32 v13, v13, v15
	ds_bpermute_b32 v15, v99, v55
	ds_bpermute_b32 v14, v99, v54
	v_cndmask_b32_e32 v7, v235, v7, vcc
	v_cmp_ne_u32_e32 vcc, s8, v77
	s_waitcnt lgkmcnt(0)
	v_fma_f32 v14, v38, v40, v14
	v_fma_f32 v15, v39, v40, v15
	v_cndmask_b32_e32 v7, v236, v7, vcc
	v_cmp_ne_u32_e32 vcc, s8, v78
	ds_bpermute_b32 v17, v98, v15
	ds_bpermute_b32 v16, v98, v14
	v_cndmask_b32_e32 v6, v236, v6, vcc
	v_cmp_ge_u32_e32 vcc, s8, v76
	s_waitcnt lgkmcnt(0)
	v_add_f32_e32 v14, v14, v16
	v_add_f32_e32 v15, v15, v17
	v_cndmask_b32_e32 v8, v235, v8, vcc
	v_cmp_ge_u32_e32 vcc, s8, v75
	ds_bpermute_b32 v17, v99, v57
	ds_bpermute_b32 v16, v99, v56
	v_cndmask_b32_e32 v9, v235, v9, vcc
	v_cmp_ne_u32_e32 vcc, s8, v75
	s_waitcnt lgkmcnt(0)
	v_fma_f32 v16, v36, v40, v16
	v_fma_f32 v17, v37, v40, v17
	v_cndmask_b32_e32 v9, v236, v9, vcc
	v_cmp_ne_u32_e32 vcc, s8, v76
	ds_bpermute_b32 v19, v98, v17
	ds_bpermute_b32 v18, v98, v16
	v_cndmask_b32_e32 v8, v236, v8, vcc
	v_cmp_ge_u32_e32 vcc, s8, v74
	s_waitcnt lgkmcnt(0)
	v_add_f32_e32 v18, v16, v18
	v_add_f32_e32 v19, v17, v19
	v_cndmask_b32_e32 v10, v235, v10, vcc
	v_cmp_ge_u32_e32 vcc, s8, v73
	v_or_b32_e32 v16, 30, v1
	v_or_b32_e32 v17, 28, v1
	v_cndmask_b32_e32 v11, v235, v11, vcc
	v_cmp_ne_u32_e32 vcc, s8, v73
	s_nop 1
	v_cndmask_b32_e32 v11, v236, v11, vcc
	v_cmp_ne_u32_e32 vcc, s8, v74
	s_nop 1
	v_cndmask_b32_e32 v10, v236, v10, vcc
	v_cmp_ge_u32_e32 vcc, s8, v72
	s_nop 1
	v_cndmask_b32_e32 v12, v235, v12, vcc
	v_cmp_ge_u32_e32 vcc, s8, v71
	s_nop 1
	v_cndmask_b32_e32 v13, v235, v13, vcc
	v_cmp_ne_u32_e32 vcc, s8, v71
	s_nop 1
	v_cndmask_b32_e32 v13, v236, v13, vcc
	v_cmp_ne_u32_e32 vcc, s8, v72
	s_nop 1
	v_cndmask_b32_e32 v12, v236, v12, vcc
	v_cmp_ge_u32_e32 vcc, s8, v70
	s_nop 1
	v_cndmask_b32_e32 v14, v235, v14, vcc
	v_cmp_ge_u32_e32 vcc, s8, v69
	s_nop 1
	v_cndmask_b32_e32 v15, v235, v15, vcc
	v_cmp_ne_u32_e32 vcc, s8, v69
	s_nop 1
	v_cndmask_b32_e32 v15, v236, v15, vcc
	v_cmp_ne_u32_e32 vcc, s8, v70
	s_nop 1
	v_cndmask_b32_e32 v14, v236, v14, vcc
	v_cmp_ge_u32_e32 vcc, s8, v16
	s_nop 1
	v_cndmask_b32_e32 v18, v235, v18, vcc
	v_cmp_ge_u32_e32 vcc, s8, v17
	s_nop 1
	v_cndmask_b32_e32 v19, v235, v19, vcc
	v_cmp_ne_u32_e32 vcc, s8, v17
	s_nop 1
	v_cndmask_b32_e32 v19, v236, v19, vcc
	v_cmp_ne_u32_e32 vcc, s8, v16
	s_nop 1
	v_cndmask_b32_e32 v18, v236, v18, vcc

; template <int BR> __device__ __forceinline__ void nsa_softmax_pv(LAS unsigned char* L, int slot, const NsaBr& c, int j, f32x16 (&sa)[2], f32x16 (&oacc)[2], float& mrun, float& lrun) {
;     ...
;     if (edge) {
; #pragma unroll
;         for (int kt = 0; kt < 2; ++kt)
; #pragma unroll
;             for (int i = 0; i < 16; ++i) { const int key = 64 * j + 32 * kt + (i & 3) + 8 * (i >> 2) + 4 * h;
;                 int pb = (t - key) >> 31;
;                 if (BR == 2) pb |= (key - (t - 511)) >> 31;
;                 const float v = sa[kt][i] + __int_as_float(pb & (int)0xF149F2CA); sa[kt][i] = v; mblk = fmaxf(mblk, v); }
;     } else {
; #pragma unroll
;         for (int kt = 0; kt < 2; ++kt)
; #pragma unroll
;             for (int i = 0; i < 16; i += 2) mblk = fmaxf(mblk, fmaxf(sa[kt][i], sa[kt][i + 1]));
;     }
;     if (BR == 1) mblk = mine ? mblk : -1e30f;
;     mblk = fmaxf(mblk, __shfl_xor(mblk, 32));
;     if (__any(mblk > mrun + NSA_DEFER)) {
;         const float mnew = fmaxf(mrun, mblk);
;         const float alpha = __builtin_amdgcn_exp2f(mrun - mnew);
;         lrun *= alpha; mrun = mnew;
; #pragma unroll
;         for (int i = 0; i < 16; ++i) { oacc[0][i] *= alpha; oacc[1][i] *= alpha; }
;     }
.LBB0_1773:
	v_add_f32_e32 v2, v2, v164
	v_add_f32_e32 v3, v3, v165
	v_add_f32_e32 v4, v4, v166
	v_add_f32_e32 v5, v5, v167
	v_max3_f32 v202, v2, s12, v3
	v_max3_f32 v202, v202, v4, v5
	v_add_f32_e32 v6, v6, v168
	v_add_f32_e32 v7, v7, v169
	v_add_f32_e32 v8, v8, v170
	v_add_f32_e32 v9, v9, v171
	v_max3_f32 v202, v202, v6, v7
	v_max3_f32 v202, v202, v8, v9
	v_add_f32_e32 v10, v10, v172
	v_add_f32_e32 v11, v11, v173
	v_add_f32_e32 v12, v12, v174
	v_add_f32_e32 v13, v13, v175
	v_max3_f32 v202, v202, v10, v11
	v_max3_f32 v202, v202, v12, v13
	v_add_f32_e32 v14, v14, v176
	v_add_f32_e32 v15, v15, v177
	v_add_f32_e32 v16, v16, v178
	v_add_f32_e32 v17, v17, v179
	v_max3_f32 v202, v202, v14, v15
	v_max3_f32 v202, v202, v16, v17
	v_add_f32_e32 v18, v18, v180
	v_add_f32_e32 v19, v19, v181
	v_add_f32_e32 v20, v20, v182
	v_add_f32_e32 v21, v21, v183
	v_max3_f32 v202, v202, v18, v19
	v_max3_f32 v202, v202, v20, v21
	v_add_f32_e32 v22, v22, v184
	v_add_f32_e32 v23, v23, v185
	v_add_f32_e32 v24, v24, v186
	v_add_f32_e32 v25, v25, v187
	v_max3_f32 v202, v202, v22, v23
	v_max3_f32 v202, v202, v24, v25
	v_add_f32_e32 v26, v26, v188
	v_add_f32_e32 v27, v27, v189
	v_add_f32_e32 v28, v28, v190
	v_add_f32_e32 v29, v29, v191
	v_max3_f32 v202, v202, v26, v27
	v_max3_f32 v202, v202, v28, v29
	v_add_f32_e32 v30, v30, v192
	v_add_f32_e32 v31, v31, v193
	v_add_f32_e32 v32, v32, v194
	v_add_f32_e32 v33, v33, v195
	v_max3_f32 v202, v202, v30, v31
	v_max3_f32 v202, v202, v32, v33
.LBB0_1774:
	s_lshl_b32 s4, 1, s31
	v_and_b32_e32 v219, s4, v217
	v_cmp_eq_u32_e64 s[94:95], 0, v219
	s_nop 1
	v_cndmask_b32_e64 v202, v202, v234, s[94:95]
	ds_bpermute_b32 v219, v205, v202
	v_max_f32_e32 v202, v202, v202
	s_waitcnt lgkmcnt(0)
	v_max_f32_e32 v219, v219, v219
	v_max_f32_e32 v202, v202, v219
	v_add_f32_e32 v219, 0x41000000, v218
	v_cmp_gt_f32_e32 vcc, v202, v219
	s_cbranch_vccz .LBB0_1776
	v_max_f32_e32 v202, v202, v202
	v_max_f32_e32 v219, v218, v218
	v_max_f32_e32 v219, v219, v202
	v_sub_f32_e32 v202, v218, v219
	v_exp_f32_e32 v202, v202
	v_mov_b32_e32 v218, v219
	v_mul_f32_e32 v133, v133, v202
	v_mul_f32_e32 v64, v64, v202
	v_mul_f32_e32 v65, v65, v202
	v_mul_f32_e32 v62, v62, v202
	v_mul_f32_e32 v63, v63, v202
	v_mul_f32_e32 v60, v60, v202
	v_mul_f32_e32 v61, v61, v202
	v_mul_f32_e32 v58, v58, v202
	v_mul_f32_e32 v59, v59, v202
	v_mul_f32_e32 v56, v56, v202
	v_mul_f32_e32 v57, v57, v202
	v_mul_f32_e32 v54, v54, v202
	v_mul_f32_e32 v55, v55, v202
	v_mul_f32_e32 v52, v52, v202
	v_mul_f32_e32 v53, v53, v202
	v_mul_f32_e32 v50, v50, v202
	v_mul_f32_e32 v51, v51, v202
	v_mul_f32_e32 v48, v48, v202
	v_mul_f32_e32 v49, v49, v202
	v_mul_f32_e32 v46, v46, v202
	v_mul_f32_e32 v47, v47, v202
	v_mul_f32_e32 v44, v44, v202
	v_mul_f32_e32 v45, v45, v202
	v_mul_f32_e32 v42, v42, v202
	v_mul_f32_e32 v43, v43, v202
	v_mul_f32_e32 v40, v40, v202
	v_mul_f32_e32 v41, v41, v202
	v_mul_f32_e32 v38, v38, v202
	v_mul_f32_e32 v39, v39, v202
	v_mul_f32_e32 v36, v36, v202
	v_mul_f32_e32 v37, v37, v202
	v_mul_f32_e32 v34, v34, v202
	v_mul_f32_e32 v35, v35, v202

; #define LAS __attribute__((address_space(3)))
; #define LDS_BARRIER() do { asm volatile("s_waitcnt lgkmcnt(0)" ::: "memory"); __builtin_amdgcn_s_barrier(); asm volatile("" ::: "memory"); } while (0)
; #define MFMA32(a, b, c) __builtin_amdgcn_mfma_f32_32x32x16_bf16((a), (b), (c), 0, 0, 0)
; #define NSA_PRIO_ON(c) do { if ((c).hiw) __builtin_amdgcn_s_setprio(3); else __builtin_amdgcn_s_setprio(1); } while (0)
; #define NSA_PRIO_OFF() __builtin_amdgcn_s_setprio(0)
; template <int BR> __device__ __forceinline__ void nsa_softmax_pv(LAS unsigned char* L, int slot, const NsaBr& c, int j, f32x16 (&sa)[2], f32x16 (&oacc)[2], float& mrun, float& lrun) {
;     ...
;     const float msub = (BR == 1 && !mine) ? 1e30f : mrun;
;     f32x2 ps2 = {0.f, 0.f}; float nmsub = -msub; asm volatile("" : "+v"(nmsub)); const f32x2 nm2 = {nmsub, nmsub};
; #pragma unroll
;     for (int kt = 0; kt < 2; ++kt) {
; #pragma unroll
;         for (int i = 0; i < 16; i += 2) { const f32x2 x = (f32x2){sa[kt][i], sa[kt][i + 1]} + nm2; sa[kt][i] = __builtin_amdgcn_exp2f(x.x); sa[kt][i + 1] = __builtin_amdgcn_exp2f(x.y); }
; #pragma unroll
;         for (int i = 0; i < 16; i += 2) ps2 += (f32x2){sa[kt][i], sa[kt][i + 1]};
;     }
;     const float psum = ps2.x + ps2.y;
;     lrun += psum;
;     NSA_PRIO_ON(c);
; #pragma unroll
;     for (int kt = 0; kt < 2; ++kt)
; #pragma unroll
;         for (int s2 = 0; s2 < 2; ++s2) { const bf16x8 pf = pack_step(sa[kt], s2);
; #pragma unroll
;             for (int dt = 0; dt < 2; ++dt) { const LAS unsigned char* vp = L + slot + 9216 + (32 * dt + r) * 136 + (32 * kt + 16 * s2 + 4 * h) * 2;
;                 const s16x4 lo = *(const LAS s16x4*)vp, hi = *(const LAS s16x4*)(vp + 16);
;                 const bf16x8 vf = __builtin_shufflevector(lo, hi, 0, 1, 2, 3, 4, 5, 6, 7);
;                 oacc[dt] = MFMA32(vf, pf, oacc[dt]); } }
;     NSA_PRIO_OFF();
; template <int BR> __device__ __forceinline__ void nsa_step(LAS unsigned char* L, const NsaBr& c, const bf16x8 (&qr)[4], int jj, int nblk, int s_cur, int s_nxt, int s_wr, ...
;     LDS_BARRIER();
;     if (jj + 2 < nblk) { nsa_kv_write(L, s_wr, c, kreg, vreg); if (jj + 3 < nblk) nsa_kv_load(c, c.jlo + jj + 3, kreg, vreg); }
.LBB0_1780:
	v_add_f32_e32 v2, v2, v202
	v_add_f32_e32 v3, v3, v202
	v_add_f32_e32 v4, v4, v202
	v_add_f32_e32 v5, v5, v202
	v_exp_f32_e32 v2, v2
	v_exp_f32_e32 v3, v3
	v_exp_f32_e32 v4, v4
	v_exp_f32_e32 v5, v5
	v_add_f32_e32 v6, v6, v202
	v_add_f32_e32 v7, v7, v202
	v_add_f32_e32 v8, v8, v202
	v_add_f32_e32 v9, v9, v202
	v_exp_f32_e32 v6, v6
	v_exp_f32_e32 v7, v7
	v_exp_f32_e32 v8, v8
	v_exp_f32_e32 v9, v9
	v_add_f32_e32 v10, v10, v202
	v_add_f32_e32 v11, v11, v202
	v_add_f32_e32 v12, v12, v202
	v_add_f32_e32 v13, v13, v202
	v_exp_f32_e32 v10, v10
	v_exp_f32_e32 v11, v11
	v_add_f32_e32 v220, 0, v2
	v_add_f32_e32 v221, 0, v3
	v_exp_f32_e32 v12, v12
	v_exp_f32_e32 v13, v13
	v_add_f32_e32 v14, v14, v202
	v_add_f32_e32 v15, v15, v202
	v_add_f32_e32 v220, v4, v220
	v_add_f32_e32 v221, v5, v221
	v_exp_f32_e32 v14, v14
	v_exp_f32_e32 v15, v15
	v_add_f32_e32 v16, v16, v202
	v_add_f32_e32 v17, v17, v202
	v_add_f32_e32 v220, v6, v220
	v_add_f32_e32 v221, v7, v221
	v_exp_f32_e32 v16, v16
	v_exp_f32_e32 v17, v17
	v_add_f32_e32 v220, v8, v220
	v_add_f32_e32 v221, v9, v221
	v_add_f32_e32 v18, v18, v202
	v_add_f32_e32 v19, v19, v202
	v_add_f32_e32 v220, v10, v220
	v_add_f32_e32 v221, v11, v221
	v_exp_f32_e32 v18, v18
	v_exp_f32_e32 v19, v19
	v_add_f32_e32 v20, v20, v202
	v_add_f32_e32 v21, v21, v202
	v_add_f32_e32 v220, v12, v220
	v_add_f32_e32 v221, v13, v221
	v_exp_f32_e32 v20, v20
	v_exp_f32_e32 v21, v21
	v_add_f32_e32 v22, v22, v202
	v_add_f32_e32 v23, v23, v202
	v_add_f32_e32 v220, v14, v220
	v_add_f32_e32 v221, v15, v221
	v_exp_f32_e32 v22, v22
	v_exp_f32_e32 v23, v23
	v_add_f32_e32 v24, v24, v202
	v_add_f32_e32 v25, v25, v202
	v_add_f32_e32 v220, v16, v220
	v_add_f32_e32 v221, v17, v221
	v_exp_f32_e32 v24, v24
	v_exp_f32_e32 v25, v25
	v_add_f32_e32 v26, v26, v202
	v_add_f32_e32 v27, v27, v202
	v_add_f32_e32 v28, v28, v202
	v_add_f32_e32 v29, v29, v202
	v_exp_f32_e32 v26, v26
	v_exp_f32_e32 v27, v27
	v_add_f32_e32 v220, v18, v220
	v_add_f32_e32 v221, v19, v221
	v_exp_f32_e32 v28, v28
	v_exp_f32_e32 v29, v29
	v_add_f32_e32 v30, v30, v202
	v_add_f32_e32 v31, v31, v202
	v_add_f32_e32 v220, v20, v220
	v_add_f32_e32 v221, v21, v221
	v_exp_f32_e32 v30, v30
	v_exp_f32_e32 v31, v31
	v_add_f32_e32 v32, v32, v202
	v_add_f32_e32 v33, v33, v202
	v_add_f32_e32 v220, v22, v220
	v_add_f32_e32 v221, v23, v221
	v_exp_f32_e32 v32, v32
	v_exp_f32_e32 v33, v33
	v_add_f32_e32 v220, v24, v220
	v_add_f32_e32 v221, v25, v221
	s_add_i32 s4, s30, 0
	v_add_f32_e32 v220, v26, v220
	v_add_f32_e32 v221, v27, v221
	v_cvt_pk_bf16_f32 v240, v2, v3
	v_cvt_pk_bf16_f32 v241, v4, v5
	v_cvt_pk_bf16_f32 v242, v6, v7
	v_cvt_pk_bf16_f32 v243, v8, v9
	s_nop 1
	v_add3_u32 v202, s4, v206, v210
	v_add_u32_e32 v219, 0x2000, v202
	v_add_u32_e32 v202, 0x3000, v202
	ds_read2_b64 v[244:247], v219 offset0:128 offset1:130
	ds_read2_b64 v[252:255], v202 offset0:160 offset1:162
	ds_read2_b64 v[6:9], v219 offset0:132 offset1:134
	s_nop 0
	v_add_f32_e32 v220, v28, v220
	v_add_f32_e32 v221, v29, v221
	s_nop 0
	v_add_f32_e32 v220, v30, v220
	v_add_f32_e32 v221, v31, v221
	s_nop 0
	v_add_f32_e32 v220, v32, v220
	v_add_f32_e32 v221, v33, v221
	s_nop 0
	v_add_f32_e32 v220, v220, v221
	v_add_f32_e32 v133, v133, v220
	s_waitcnt lgkmcnt(2)
	v_mfma_f32_32x32x16_bf16 v[34:49], v[244:247], v[240:243], v[34:49]
	s_waitcnt lgkmcnt(1)
	v_mfma_f32_32x32x16_bf16 v[50:65], v[252:255], v[240:243], v[50:65]
	v_cvt_pk_bf16_f32 v240, v10, v11
	v_cvt_pk_bf16_f32 v241, v12, v13
	v_cvt_pk_bf16_f32 v242, v14, v15
	v_cvt_pk_bf16_f32 v243, v16, v17
	s_nop 1
	ds_read2_b64 v[244:247], v202 offset0:164 offset1:166
	ds_read2_b64 v[252:255], v219 offset0:136 offset1:138
	ds_read2_b64 v[10:13], v202 offset0:168 offset1:170
	s_waitcnt lgkmcnt(3)
	v_mfma_f32_32x32x16_bf16 v[34:49], v[6:9], v[240:243], v[34:49]
	s_waitcnt lgkmcnt(2)
	v_mfma_f32_32x32x16_bf16 v[50:65], v[244:247], v[240:243], v[50:65]
	v_cvt_pk_bf16_f32 v240, v18, v19
	v_cvt_pk_bf16_f32 v241, v20, v21
	v_cvt_pk_bf16_f32 v242, v22, v23
	v_cvt_pk_bf16_f32 v243, v24, v25
	s_nop 1
	ds_read2_b64 v[6:9], v219 offset0:140 offset1:142
	ds_read2_b64 v[244:247], v202 offset0:172 offset1:174
	s_waitcnt lgkmcnt(3)
	v_mfma_f32_32x32x16_bf16 v[34:49], v[252:255], v[240:243], v[34:49]
	s_waitcnt lgkmcnt(2)
	v_mfma_f32_32x32x16_bf16 v[50:65], v[10:13], v[240:243], v[50:65]
	v_cvt_pk_bf16_f32 v240, v26, v27
	v_cvt_pk_bf16_f32 v241, v28, v29
	v_cvt_pk_bf16_f32 v242, v30, v31
	v_cvt_pk_bf16_f32 v243, v32, v33
	s_nop 1
	s_waitcnt lgkmcnt(1)
	v_mfma_f32_32x32x16_bf16 v[34:49], v[6:9], v[240:243], v[34:49]
	s_waitcnt lgkmcnt(0)
	v_mfma_f32_32x32x16_bf16 v[50:65], v[244:247], v[240:243], v[50:65]
	s_setprio 0
	s_andn2_b64 vcc, exec, s[26:27]
	s_cbranch_vccnz .LBB0_1803
	s_waitcnt lgkmcnt(0)
	s_barrier
	s_add_i32 s5, s31, 3
	s_cmp_gt_u32 s5, s8
	s_cbranch_scc1 .LBB0_1784
	v_add3_u32 v202, s4, v207, v198
	s_waitcnt vmcnt(1)
	ds_write_b128 v202, v[114:117]
	v_add_u32_e32 v202, s4, v208
	s_add_i32 s4, s31, 4
	v_add3_u32 v202, v202, v198, s13
	s_cmp_gt_u32 s4, s8
	s_waitcnt vmcnt(0)
	ds_write2_b64 v202, v[118:119], v[120:121] offset1:1
	s_cbranch_scc1 .LBB0_1784
	v_lshl_add_u64 v[114:115], v[196:197], 0, v[198:199]
	v_add_co_u32_e32 v114, vcc, 0x6e008000, v114
	v_lshl_add_u64 v[118:119], v[200:201], 0, v[198:199]
	s_nop 0
	v_addc_co_u32_e32 v115, vcc, 0, v115, vcc
	v_add_co_u32_e32 v118, vcc, 0x6e400000, v118
	global_load_dwordx4 v[114:117], v[114:115], off
	s_nop 0
	v_addc_co_u32_e32 v119, vcc, 0, v119, vcc
	global_load_dwordx4 v[118:121], v[118:119], off offset:512

; template <int BR> __device__ __forceinline__ void nsa_softmax_pv(LAS unsigned char* L, int slot, const NsaBr& c, int j, f32x16 (&sa)[2], f32x16 (&oacc)[2], float& mrun, float& lrun) {
;     ...
;     const bool edge = (j == c.qt) || (BR == 2 && c.qt >= 8 && j == c.jlo);
;     if (edge) {
; #pragma unroll
;         for (int kt = 0; kt < 2; ++kt)
; #pragma unroll
;             for (int i = 0; i < 16; ++i) { const int key = 64 * j + 32 * kt + (i & 3) + 8 * (i >> 2) + 4 * h;
;                 int pb = (t - key) >> 31;
;                 if (BR == 2) pb |= (key - (t - 511)) >> 31;
;                 const float v = sa[kt][i] + __int_as_float(pb & (int)0xF149F2CA); sa[kt][i] = v; mblk = fmaxf(mblk, v); }
;     } else {
; #pragma unroll
;         for (int kt = 0; kt < 2; ++kt)
; #pragma unroll
;             for (int i = 0; i < 16; i += 2) mblk = fmaxf(mblk, fmaxf(sa[kt][i], sa[kt][i + 1]));
;     }
;     if (BR == 1) mblk = mine ? mblk : -1e30f;
;     mblk = fmaxf(mblk, __shfl_xor(mblk, 32));
;     if (__any(mblk > mrun + NSA_DEFER)) {
;         const float mnew = fmaxf(mrun, mblk);
;         const float alpha = __builtin_amdgcn_exp2f(mrun - mnew);
;         lrun *= alpha; mrun = mnew;
; #pragma unroll
;         for (int i = 0; i < 16; ++i) { oacc[0][i] *= alpha; oacc[1][i] *= alpha; }
;     }
;     const float msub = (BR == 1 && !mine) ? 1e30f : mrun;
.LBB0_1795:
	v_add_f32_e32 v66, v66, v164
	v_add_f32_e32 v67, v67, v165
	v_add_f32_e32 v68, v68, v166
	v_add_f32_e32 v69, v69, v167
	v_max3_f32 v219, v66, s12, v67
	v_max3_f32 v219, v219, v68, v69
	v_add_f32_e32 v70, v70, v168
	v_add_f32_e32 v71, v71, v169
	v_add_f32_e32 v72, v72, v170
	v_add_f32_e32 v73, v73, v171
	v_max3_f32 v219, v219, v70, v71
	v_max3_f32 v219, v219, v72, v73
	v_add_f32_e32 v74, v74, v172
	v_add_f32_e32 v75, v75, v173
	v_add_f32_e32 v76, v76, v174
	v_add_f32_e32 v77, v77, v175
	v_max3_f32 v219, v219, v74, v75
	v_max3_f32 v219, v219, v76, v77
	v_add_f32_e32 v78, v78, v176
	v_add_f32_e32 v79, v79, v177
	v_add_f32_e32 v80, v80, v178
	v_add_f32_e32 v81, v81, v179
	v_max3_f32 v219, v219, v78, v79
	v_max3_f32 v219, v219, v80, v81
	v_add_f32_e32 v82, v82, v180
	v_add_f32_e32 v83, v83, v181
	v_add_f32_e32 v84, v84, v182
	v_add_f32_e32 v85, v85, v183
	v_max3_f32 v219, v219, v82, v83
	v_max3_f32 v219, v219, v84, v85
	v_add_f32_e32 v86, v86, v184
	v_add_f32_e32 v87, v87, v185
	v_add_f32_e32 v88, v88, v186
	v_add_f32_e32 v89, v89, v187
	v_max3_f32 v219, v219, v86, v87
	v_max3_f32 v219, v219, v88, v89
	v_add_f32_e32 v90, v90, v188
	v_add_f32_e32 v91, v91, v189
	v_add_f32_e32 v92, v92, v190
	v_add_f32_e32 v93, v93, v191
	v_max3_f32 v219, v219, v90, v91
	v_max3_f32 v219, v219, v92, v93
	v_add_f32_e32 v94, v94, v192
	v_add_f32_e32 v95, v95, v193
	v_add_f32_e32 v96, v96, v194
	v_add_f32_e32 v97, v97, v195
	v_max3_f32 v219, v219, v94, v95
	v_max3_f32 v219, v219, v96, v97
.LBB0_1796:
	s_lshl_b32 s4, 2, s31
	v_and_b32_e32 v220, s4, v217
	v_cmp_eq_u32_e64 s[94:95], 0, v220
	s_nop 1
	v_cndmask_b32_e64 v219, v219, v234, s[94:95]
	ds_bpermute_b32 v220, v205, v219
	v_max_f32_e32 v219, v219, v219
	s_waitcnt lgkmcnt(0)
	v_max_f32_e32 v220, v220, v220
	v_max_f32_e32 v219, v219, v220
	v_add_f32_e32 v220, 0x41000000, v218
	v_cmp_gt_f32_e32 vcc, v219, v220
	s_cbranch_vccz .LBB0_1798
	v_max_f32_e32 v202, v219, v219
	v_max_f32_e32 v219, v218, v218
	v_max_f32_e32 v219, v219, v202
	v_sub_f32_e32 v202, v218, v219
	v_exp_f32_e32 v202, v202
	v_mov_b32_e32 v218, v219
	v_mul_f32_e32 v133, v133, v202
	v_mul_f32_e32 v64, v64, v202
	v_mul_f32_e32 v65, v65, v202
	v_mul_f32_e32 v62, v62, v202
	v_mul_f32_e32 v63, v63, v202
	v_mul_f32_e32 v60, v60, v202
	v_mul_f32_e32 v61, v61, v202
	v_mul_f32_e32 v58, v58, v202
	v_mul_f32_e32 v59, v59, v202
	v_mul_f32_e32 v56, v56, v202
	v_mul_f32_e32 v57, v57, v202
	v_mul_f32_e32 v54, v54, v202
	v_mul_f32_e32 v55, v55, v202
	v_mul_f32_e32 v52, v52, v202
	v_mul_f32_e32 v53, v53, v202
	v_mul_f32_e32 v50, v50, v202
	v_mul_f32_e32 v51, v51, v202
	v_mul_f32_e32 v48, v48, v202
	v_mul_f32_e32 v49, v49, v202
	v_mul_f32_e32 v46, v46, v202
	v_mul_f32_e32 v47, v47, v202
	v_mul_f32_e32 v44, v44, v202
	v_mul_f32_e32 v45, v45, v202
	v_mul_f32_e32 v42, v42, v202
	v_mul_f32_e32 v43, v43, v202
	v_mul_f32_e32 v40, v40, v202
	v_mul_f32_e32 v41, v41, v202
	v_mul_f32_e32 v38, v38, v202
	v_mul_f32_e32 v39, v39, v202
	v_mul_f32_e32 v36, v36, v202
	v_mul_f32_e32 v37, v37, v202
	v_mul_f32_e32 v34, v34, v202
	v_mul_f32_e32 v35, v35, v202
	v_xor_b32_e32 v202, 0x80000000, v219

; #define LAS __attribute__((address_space(3)))
; #define MFMA32(a, b, c) __builtin_amdgcn_mfma_f32_32x32x16_bf16((a), (b), (c), 0, 0, 0)
; #define NSA_PRIO_ON(c) do { if ((c).hiw) __builtin_amdgcn_s_setprio(3); else __builtin_amdgcn_s_setprio(1); } while (0)
; #define NSA_PRIO_OFF() __builtin_amdgcn_s_setprio(0)
; template <int BR> __device__ __forceinline__ void nsa_softmax_pv(LAS unsigned char* L, int slot, const NsaBr& c, int j, f32x16 (&sa)[2], f32x16 (&oacc)[2], float& mrun, float& lrun) {
;     ...
;     const float msub = (BR == 1 && !mine) ? 1e30f : mrun;
;     f32x2 ps2 = {0.f, 0.f}; float nmsub = -msub; asm volatile("" : "+v"(nmsub)); const f32x2 nm2 = {nmsub, nmsub};
; #pragma unroll
;     for (int kt = 0; kt < 2; ++kt) {
; #pragma unroll
;         for (int i = 0; i < 16; i += 2) { const f32x2 x = (f32x2){sa[kt][i], sa[kt][i + 1]} + nm2; sa[kt][i] = __builtin_amdgcn_exp2f(x.x); sa[kt][i + 1] = __builtin_amdgcn_exp2f(x.y); }
; #pragma unroll
;         for (int i = 0; i < 16; i += 2) ps2 += (f32x2){sa[kt][i], sa[kt][i + 1]};
;     }
;     const float psum = ps2.x + ps2.y;
;     lrun += psum;
;     NSA_PRIO_ON(c);
; #pragma unroll
;     for (int kt = 0; kt < 2; ++kt)
; #pragma unroll
;         for (int s2 = 0; s2 < 2; ++s2) { const bf16x8 pf = pack_step(sa[kt], s2);
; #pragma unroll
;             for (int dt = 0; dt < 2; ++dt) { const LAS unsigned char* vp = L + slot + 9216 + (32 * dt + r) * 136 + (32 * kt + 16 * s2 + 4 * h) * 2;
;                 const s16x4 lo = *(const LAS s16x4*)vp, hi = *(const LAS s16x4*)(vp + 16);
;                 const bf16x8 vf = __builtin_shufflevector(lo, hi, 0, 1, 2, 3, 4, 5, 6, 7);
;                 oacc[dt] = MFMA32(vf, pf, oacc[dt]); } }
;     NSA_PRIO_OFF();
.LBB0_1802:
	v_add_f32_e32 v66, v66, v202
	v_add_f32_e32 v67, v67, v202
	v_add_f32_e32 v68, v68, v202
	v_add_f32_e32 v69, v69, v202
	v_exp_f32_e32 v66, v66
	v_exp_f32_e32 v67, v67
	v_exp_f32_e32 v68, v68
	v_exp_f32_e32 v69, v69
	v_add_f32_e32 v70, v70, v202
	v_add_f32_e32 v71, v71, v202
	v_add_f32_e32 v72, v72, v202
	v_add_f32_e32 v73, v73, v202
	v_exp_f32_e32 v70, v70
	v_exp_f32_e32 v71, v71
	v_exp_f32_e32 v72, v72
	v_exp_f32_e32 v73, v73
	v_add_f32_e32 v74, v74, v202
	v_add_f32_e32 v75, v75, v202
	v_add_f32_e32 v76, v76, v202
	v_add_f32_e32 v77, v77, v202
	v_exp_f32_e32 v74, v74
	v_exp_f32_e32 v75, v75
	v_add_f32_e32 v220, 0, v66
	v_add_f32_e32 v221, 0, v67
	v_exp_f32_e32 v76, v76
	v_exp_f32_e32 v77, v77
	v_add_f32_e32 v78, v78, v202
	v_add_f32_e32 v79, v79, v202
	v_add_f32_e32 v220, v68, v220
	v_add_f32_e32 v221, v69, v221
	v_exp_f32_e32 v78, v78
	v_exp_f32_e32 v79, v79
	v_add_f32_e32 v80, v80, v202
	v_add_f32_e32 v81, v81, v202
	v_add_f32_e32 v220, v70, v220
	v_add_f32_e32 v221, v71, v221
	v_exp_f32_e32 v80, v80
	v_exp_f32_e32 v81, v81
	v_add_f32_e32 v220, v72, v220
	v_add_f32_e32 v221, v73, v221
	v_add_f32_e32 v82, v82, v202
	v_add_f32_e32 v83, v83, v202
	v_add_f32_e32 v220, v74, v220
	v_add_f32_e32 v221, v75, v221
	v_exp_f32_e32 v82, v82
	v_exp_f32_e32 v83, v83
	v_add_f32_e32 v84, v84, v202
	v_add_f32_e32 v85, v85, v202
	v_add_f32_e32 v220, v76, v220
	v_add_f32_e32 v221, v77, v221
	v_exp_f32_e32 v84, v84
	v_exp_f32_e32 v85, v85
	v_add_f32_e32 v86, v86, v202
	v_add_f32_e32 v87, v87, v202
	v_add_f32_e32 v220, v78, v220
	v_add_f32_e32 v221, v79, v221
	v_exp_f32_e32 v86, v86
	v_exp_f32_e32 v87, v87
	v_add_f32_e32 v88, v88, v202
	v_add_f32_e32 v89, v89, v202
	v_add_f32_e32 v220, v80, v220
	v_add_f32_e32 v221, v81, v221
	v_exp_f32_e32 v88, v88
	v_exp_f32_e32 v89, v89
	v_add_f32_e32 v90, v90, v202
	v_add_f32_e32 v91, v91, v202
	v_add_f32_e32 v92, v92, v202
	v_add_f32_e32 v93, v93, v202
	v_exp_f32_e32 v90, v90
	v_exp_f32_e32 v91, v91
	v_add_f32_e32 v220, v82, v220
	v_add_f32_e32 v221, v83, v221
	v_exp_f32_e32 v92, v92
	v_exp_f32_e32 v93, v93
	v_add_f32_e32 v94, v94, v202
	v_add_f32_e32 v95, v95, v202
	v_add_f32_e32 v220, v84, v220
	v_add_f32_e32 v221, v85, v221
	v_exp_f32_e32 v94, v94
	v_exp_f32_e32 v95, v95
	v_add_f32_e32 v96, v96, v202
	v_add_f32_e32 v97, v97, v202
	v_add_f32_e32 v220, v86, v220
	v_add_f32_e32 v221, v87, v221
	v_exp_f32_e32 v96, v96
	v_exp_f32_e32 v97, v97
	v_add_f32_e32 v220, v88, v220
	v_add_f32_e32 v221, v89, v221
	v_cvt_pk_bf16_f32 v240, v66, v67
	v_cvt_pk_bf16_f32 v241, v68, v69
	v_cvt_pk_bf16_f32 v242, v70, v71
	v_cvt_pk_bf16_f32 v243, v72, v73
	s_nop 1
	v_add_u32_e32 v202, s10, v211
	v_add_u32_e32 v219, 0x2000, v202
	v_add_u32_e32 v202, 0x3000, v202
	ds_read2_b64 v[244:247], v219 offset0:128 offset1:130
	ds_read2_b64 v[252:255], v202 offset0:160 offset1:162
	ds_read2_b64 v[70:73], v219 offset0:132 offset1:134
	s_nop 0
	v_add_f32_e32 v220, v90, v220
	v_add_f32_e32 v221, v91, v221
	s_nop 0
	v_add_f32_e32 v220, v92, v220
	v_add_f32_e32 v221, v93, v221
	s_nop 0
	v_add_f32_e32 v220, v94, v220
	v_add_f32_e32 v221, v95, v221
	s_nop 0
	v_add_f32_e32 v220, v96, v220
	v_add_f32_e32 v221, v97, v221
	s_nop 0
	v_add_f32_e32 v220, v220, v221
	v_add_f32_e32 v133, v133, v220
	s_waitcnt lgkmcnt(2)
	v_mfma_f32_32x32x16_bf16 v[34:49], v[244:247], v[240:243], v[34:49]
	s_waitcnt lgkmcnt(1)
	v_mfma_f32_32x32x16_bf16 v[50:65], v[252:255], v[240:243], v[50:65]
	v_cvt_pk_bf16_f32 v240, v74, v75
	v_cvt_pk_bf16_f32 v241, v76, v77
	v_cvt_pk_bf16_f32 v242, v78, v79
	v_cvt_pk_bf16_f32 v243, v80, v81
	s_nop 1
	ds_read2_b64 v[244:247], v202 offset0:164 offset1:166
	ds_read2_b64 v[252:255], v219 offset0:136 offset1:138
	ds_read2_b64 v[74:77], v202 offset0:168 offset1:170
	s_waitcnt lgkmcnt(3)
	v_mfma_f32_32x32x16_bf16 v[34:49], v[70:73], v[240:243], v[34:49]
	s_waitcnt lgkmcnt(2)
	v_mfma_f32_32x32x16_bf16 v[50:65], v[244:247], v[240:243], v[50:65]
	v_cvt_pk_bf16_f32 v240, v82, v83
	v_cvt_pk_bf16_f32 v241, v84, v85
	v_cvt_pk_bf16_f32 v242, v86, v87
	v_cvt_pk_bf16_f32 v243, v88, v89
	s_nop 1
	ds_read2_b64 v[70:73], v219 offset0:140 offset1:142
	ds_read2_b64 v[244:247], v202 offset0:172 offset1:174
	s_waitcnt lgkmcnt(3)
	v_mfma_f32_32x32x16_bf16 v[34:49], v[252:255], v[240:243], v[34:49]
	s_waitcnt lgkmcnt(2)
	v_mfma_f32_32x32x16_bf16 v[50:65], v[74:77], v[240:243], v[50:65]
	v_cvt_pk_bf16_f32 v240, v90, v91
	v_cvt_pk_bf16_f32 v241, v92, v93
	v_cvt_pk_bf16_f32 v242, v94, v95
	v_cvt_pk_bf16_f32 v243, v96, v97
	s_nop 1
	s_waitcnt lgkmcnt(1)
	v_mfma_f32_32x32x16_bf16 v[34:49], v[70:73], v[240:243], v[34:49]
	s_waitcnt lgkmcnt(0)
	v_mfma_f32_32x32x16_bf16 v[50:65], v[244:247], v[240:243], v[50:65]
	s_setprio 0

; template <int BR> __device__ __forceinline__ void nsa_softmax_pv(LAS unsigned char* L, int slot, const NsaBr& c, int j, f32x16 (&sa)[2], f32x16 (&oacc)[2], float& mrun, float& lrun) {
;     ...
;     if (edge) {
; #pragma unroll
;         for (int kt = 0; kt < 2; ++kt)
; #pragma unroll
;             for (int i = 0; i < 16; ++i) { const int key = 64 * j + 32 * kt + (i & 3) + 8 * (i >> 2) + 4 * h;
;                 int pb = (t - key) >> 31;
;                 if (BR == 2) pb |= (key - (t - 511)) >> 31;
;                 const float v = sa[kt][i] + __int_as_float(pb & (int)0xF149F2CA); sa[kt][i] = v; mblk = fmaxf(mblk, v); }
.LBB0_1826:
	s_andn2_b64 vcc, exec, s[0:1]
	s_cbranch_vccnz .LBB0_1828
	v_add_u32_e32 v122, s4, v154
	v_cmp_lt_i32_e32 vcc, v128, v122
	v_cmp_lt_i32_e64 s[0:1], v122, v162
	s_or_b64 vcc, vcc, s[0:1]
	v_cndmask_b32_e32 v138, 0, v234, vcc
	v_add_f32_e32 v34, v34, v138
	v_add_u32_e32 v138, 1, v122
	v_cmp_le_i32_e32 vcc, v128, v122
	v_cmp_lt_i32_e64 s[0:1], v138, v162
	s_or_b64 vcc, vcc, s[0:1]
	v_or_b32_e32 v175, 3, v122
	v_cndmask_b32_e32 v138, 0, v234, vcc
	v_or_b32_e32 v176, 2, v122
	v_cmp_lt_i32_e32 vcc, v1, v175
	v_cmp_lt_i32_e64 s[40:41], v175, v123
	v_cmp_lt_i32_e64 s[0:1], v128, v176
	v_cmp_lt_i32_e64 s[42:43], v176, v162
	s_or_b64 vcc, vcc, s[40:41]
	v_cndmask_b32_e32 v177, 0, v234, vcc
	s_or_b64 vcc, s[0:1], s[42:43]
	v_cndmask_b32_e32 v176, 0, v234, vcc
	v_or_b32_e32 v175, 9, v122
	v_add_f32_e32 v36, v36, v176
	v_add_f32_e32 v37, v37, v177
	v_or_b32_e32 v176, 8, v122
	v_cmp_lt_i32_e32 vcc, v1, v175
	v_cmp_lt_i32_e64 s[40:41], v175, v123
	v_cmp_lt_i32_e64 s[0:1], v128, v176
	v_cmp_lt_i32_e64 s[42:43], v176, v162
	s_or_b64 vcc, vcc, s[40:41]
	v_cndmask_b32_e32 v177, 0, v234, vcc
	s_or_b64 vcc, s[0:1], s[42:43]
	v_cndmask_b32_e32 v176, 0, v234, vcc
	v_or_b32_e32 v175, 11, v122
	v_add_f32_e32 v38, v38, v176
	v_add_f32_e32 v39, v39, v177
	v_or_b32_e32 v176, 10, v122
	v_cmp_lt_i32_e32 vcc, v1, v175
	v_cmp_lt_i32_e64 s[40:41], v175, v123
	v_cmp_lt_i32_e64 s[0:1], v128, v176
	v_cmp_lt_i32_e64 s[42:43], v176, v162
	s_or_b64 vcc, vcc, s[40:41]
	v_cndmask_b32_e32 v177, 0, v234, vcc
	s_or_b64 vcc, s[0:1], s[42:43]
	v_cndmask_b32_e32 v176, 0, v234, vcc
	v_or_b32_e32 v175, 17, v122
	v_add_f32_e32 v40, v40, v176
	v_add_f32_e32 v41, v41, v177
	v_or_b32_e32 v176, 16, v122
	v_cmp_lt_i32_e32 vcc, v1, v175
	v_cmp_lt_i32_e64 s[40:41], v175, v123
	v_cmp_lt_i32_e64 s[0:1], v128, v176
	v_cmp_lt_i32_e64 s[42:43], v176, v162
	s_or_b64 vcc, vcc, s[40:41]
	v_cndmask_b32_e32 v177, 0, v234, vcc
	s_or_b64 vcc, s[0:1], s[42:43]
	v_cndmask_b32_e32 v176, 0, v234, vcc
	v_or_b32_e32 v175, 19, v122
	v_add_f32_e32 v42, v42, v176
	v_add_f32_e32 v43, v43, v177
	v_or_b32_e32 v176, 18, v122
	v_cmp_lt_i32_e32 vcc, v1, v175
	v_cmp_lt_i32_e64 s[40:41], v175, v123
	v_cmp_lt_i32_e64 s[0:1], v128, v176
	v_cmp_lt_i32_e64 s[42:43], v176, v162
	s_or_b64 vcc, vcc, s[40:41]
	v_cndmask_b32_e32 v177, 0, v234, vcc
	s_or_b64 vcc, s[0:1], s[42:43]
	v_cndmask_b32_e32 v176, 0, v234, vcc
	v_or_b32_e32 v175, 25, v122
	v_add_f32_e32 v44, v44, v176
	v_add_f32_e32 v45, v45, v177
	v_or_b32_e32 v176, 24, v122
	v_cmp_lt_i32_e32 vcc, v1, v175
	v_cmp_lt_i32_e64 s[40:41], v175, v123
	v_cmp_lt_i32_e64 s[0:1], v128, v176
	v_cmp_lt_i32_e64 s[42:43], v176, v162
	s_or_b64 vcc, vcc, s[40:41]
	v_cndmask_b32_e32 v177, 0, v234, vcc
	s_or_b64 vcc, s[0:1], s[42:43]
	v_cndmask_b32_e32 v176, 0, v234, vcc
	v_or_b32_e32 v175, 27, v122
	v_add_f32_e32 v46, v46, v176
	v_add_f32_e32 v47, v47, v177
	v_or_b32_e32 v176, 26, v122
	v_cmp_lt_i32_e32 vcc, v1, v175
	v_cmp_lt_i32_e64 s[40:41], v175, v123
	v_cmp_lt_i32_e64 s[0:1], v128, v176
	v_cmp_lt_i32_e64 s[42:43], v176, v162
	s_or_b64 vcc, vcc, s[40:41]
	v_cndmask_b32_e32 v177, 0, v234, vcc
	s_or_b64 vcc, s[0:1], s[42:43]
	v_add_u32_e32 v175, 32, v122
	v_cndmask_b32_e32 v176, 0, v234, vcc
	v_cmp_lt_i32_e32 vcc, v128, v175
	v_cmp_lt_i32_e64 s[0:1], v175, v162
	s_or_b64 vcc, vcc, s[0:1]
	v_add_f32_e32 v48, v48, v176
	v_add_f32_e32 v49, v49, v177
	v_cndmask_b32_e32 v176, 0, v234, vcc
	v_add_f32_e32 v50, v50, v176
	v_add_u32_e32 v176, 33, v122
	v_cmp_le_i32_e32 vcc, v128, v175
	v_cmp_lt_i32_e64 s[0:1], v176, v162
	s_or_b64 vcc, vcc, s[0:1]
	v_cndmask_b32_e32 v175, 0, v234, vcc
	v_add_f32_e32 v51, v51, v175
	v_or_b32_e32 v175, 35, v122
	v_or_b32_e32 v176, 34, v122
	v_cmp_lt_i32_e32 vcc, v1, v175
	v_cmp_lt_i32_e64 s[40:41], v175, v123
	v_cmp_lt_i32_e64 s[0:1], v128, v176
	v_cmp_lt_i32_e64 s[42:43], v176, v162
	s_or_b64 vcc, vcc, s[40:41]
	v_cndmask_b32_e32 v177, 0, v234, vcc
	s_or_b64 vcc, s[0:1], s[42:43]
	v_cndmask_b32_e32 v176, 0, v234, vcc
	v_or_b32_e32 v175, 41, v122
	v_add_f32_e32 v52, v52, v176
	v_add_f32_e32 v53, v53, v177
	v_or_b32_e32 v176, 40, v122
	v_cmp_lt_i32_e32 vcc, v1, v175
	v_cmp_lt_i32_e64 s[40:41], v175, v123
	v_cmp_lt_i32_e64 s[0:1], v128, v176
	v_cmp_lt_i32_e64 s[42:43], v176, v162
	s_or_b64 vcc, vcc, s[40:41]
	v_cndmask_b32_e32 v177, 0, v234, vcc
	s_or_b64 vcc, s[0:1], s[42:43]
	v_cndmask_b32_e32 v176, 0, v234, vcc
	v_or_b32_e32 v175, 43, v122
	v_add_f32_e32 v54, v54, v176
	v_add_f32_e32 v55, v55, v177
	v_or_b32_e32 v176, 42, v122
	v_cmp_lt_i32_e32 vcc, v1, v175
	v_cmp_lt_i32_e64 s[40:41], v175, v123
	v_cmp_lt_i32_e64 s[0:1], v128, v176
	v_cmp_lt_i32_e64 s[42:43], v176, v162
	s_or_b64 vcc, vcc, s[40:41]
	v_cndmask_b32_e32 v177, 0, v234, vcc
	s_or_b64 vcc, s[0:1], s[42:43]
	v_cndmask_b32_e32 v176, 0, v234, vcc
	v_or_b32_e32 v175, 49, v122
	v_add_f32_e32 v35, v35, v138
	v_add_f32_e32 v56, v56, v176
	v_add_f32_e32 v57, v57, v177
	v_or_b32_e32 v176, 48, v122
	v_cmp_lt_i32_e32 vcc, v1, v175
	v_cmp_lt_i32_e64 s[40:41], v175, v123
	v_max3_f32 v138, v34, s12, v35
	v_cmp_lt_i32_e64 s[0:1], v128, v176
	v_cmp_lt_i32_e64 s[42:43], v176, v162
	s_or_b64 vcc, vcc, s[40:41]
	v_max3_f32 v138, v138, v36, v37
	v_cndmask_b32_e32 v177, 0, v234, vcc
	s_or_b64 vcc, s[0:1], s[42:43]
	v_max3_f32 v138, v138, v38, v39
	v_cndmask_b32_e32 v176, 0, v234, vcc
	v_or_b32_e32 v175, 51, v122
	v_max3_f32 v138, v138, v40, v41
	v_add_f32_e32 v58, v58, v176
	v_add_f32_e32 v59, v59, v177
	v_or_b32_e32 v176, 50, v122
	v_cmp_lt_i32_e32 vcc, v1, v175
	v_cmp_lt_i32_e64 s[40:41], v175, v123
	v_max3_f32 v138, v138, v42, v43
	v_cmp_lt_i32_e64 s[0:1], v128, v176
	v_cmp_lt_i32_e64 s[42:43], v176, v162
	s_or_b64 vcc, vcc, s[40:41]
	v_max3_f32 v138, v138, v44, v45
	v_cndmask_b32_e32 v177, 0, v234, vcc
	s_or_b64 vcc, s[0:1], s[42:43]
	v_max3_f32 v138, v138, v46, v47
	v_cndmask_b32_e32 v176, 0, v234, vcc
	v_or_b32_e32 v175, 57, v122
	v_max3_f32 v138, v138, v48, v49
	v_add_f32_e32 v60, v60, v176
	v_add_f32_e32 v61, v61, v177
	v_or_b32_e32 v176, 56, v122
	v_cmp_lt_i32_e32 vcc, v1, v175
	v_cmp_lt_i32_e64 s[40:41], v175, v123
	v_max3_f32 v138, v138, v50, v51
	v_cmp_lt_i32_e64 s[0:1], v128, v176
	v_cmp_lt_i32_e64 s[42:43], v176, v162
	s_or_b64 vcc, vcc, s[40:41]
	v_max3_f32 v138, v138, v52, v53
	v_cndmask_b32_e32 v177, 0, v234, vcc
	s_or_b64 vcc, s[0:1], s[42:43]
	v_or_b32_e32 v175, 59, v122
	v_max3_f32 v138, v138, v54, v55
	v_cndmask_b32_e32 v176, 0, v234, vcc
	v_or_b32_e32 v122, 58, v122
	v_cmp_lt_i32_e32 vcc, v1, v175
	v_cmp_lt_i32_e64 s[40:41], v175, v123
	v_max3_f32 v138, v138, v56, v57
	v_cmp_lt_i32_e64 s[0:1], v128, v122
	v_cmp_lt_i32_e64 s[42:43], v122, v162
	s_or_b64 vcc, vcc, s[40:41]
	v_max3_f32 v138, v138, v58, v59
	v_add_f32_e32 v62, v62, v176
	v_add_f32_e32 v63, v63, v177
	v_cndmask_b32_e32 v177, 0, v234, vcc
	s_or_b64 vcc, s[0:1], s[42:43]
	v_max3_f32 v138, v138, v60, v61
	v_cndmask_b32_e32 v176, 0, v234, vcc
	v_max3_f32 v138, v138, v62, v63
	v_add_f32_e32 v64, v64, v176
	v_add_f32_e32 v65, v65, v177
	s_nop 0
	v_max3_f32 v122, v138, v64, v65
; template <int BR> __device__ __forceinline__ void nsa_softmax_pv(LAS unsigned char* L, int slot, const NsaBr& c, int j, f32x16 (&sa)[2], f32x16 (&oacc)[2], float& mrun, float& lrun) {
;     ...
;     mblk = fmaxf(mblk, __shfl_xor(mblk, 32));
;     if (__any(mblk > mrun + NSA_DEFER)) {
;         const float mnew = fmaxf(mrun, mblk);
;         const float alpha = __builtin_amdgcn_exp2f(mrun - mnew);
;         lrun *= alpha; mrun = mnew;
; #pragma unroll
;         for (int i = 0; i < 16; ++i) { oacc[0][i] *= alpha; oacc[1][i] *= alpha; }
;     }
.LBB0_1828:
	ds_bpermute_b32 v138, v205, v122
	v_max_f32_e32 v122, v122, v122
	s_waitcnt lgkmcnt(0)
	v_max_f32_e32 v138, v138, v138
	v_max_f32_e32 v122, v122, v138
	v_add_f32_e32 v138, 0x41000000, v174
	v_cmp_gt_f32_e32 vcc, v122, v138
	s_cbranch_vccz .LBB0_1830
	v_max_f32_e32 v122, v122, v122
	v_max_f32_e32 v138, v174, v174
	v_max_f32_e32 v138, v138, v122
	v_sub_f32_e32 v122, v174, v138
	v_exp_f32_e32 v122, v122
	v_mov_b32_e32 v174, v138
	v_mul_f32_e32 v155, v155, v122
	v_mul_f32_e32 v32, v32, v122
	v_mul_f32_e32 v33, v33, v122
	v_mul_f32_e32 v30, v30, v122
	v_mul_f32_e32 v31, v31, v122
	v_mul_f32_e32 v28, v28, v122
	v_mul_f32_e32 v29, v29, v122
	v_mul_f32_e32 v26, v26, v122
	v_mul_f32_e32 v27, v27, v122
	v_mul_f32_e32 v24, v24, v122
	v_mul_f32_e32 v25, v25, v122
	v_mul_f32_e32 v22, v22, v122
	v_mul_f32_e32 v23, v23, v122
	v_mul_f32_e32 v20, v20, v122
	v_mul_f32_e32 v21, v21, v122
	v_mul_f32_e32 v18, v18, v122
	v_mul_f32_e32 v19, v19, v122
	v_mul_f32_e32 v16, v16, v122
	v_mul_f32_e32 v17, v17, v122
	v_mul_f32_e32 v14, v14, v122
	v_mul_f32_e32 v15, v15, v122
	v_mul_f32_e32 v12, v12, v122
	v_mul_f32_e32 v13, v13, v122
	v_mul_f32_e32 v10, v10, v122
	v_mul_f32_e32 v11, v11, v122
	v_mul_f32_e32 v8, v8, v122
	v_mul_f32_e32 v9, v9, v122
	v_mul_f32_e32 v6, v6, v122
	v_mul_f32_e32 v7, v7, v122
	v_mul_f32_e32 v4, v4, v122
	v_mul_f32_e32 v5, v5, v122
	v_mul_f32_e32 v2, v2, v122
	v_mul_f32_e32 v3, v3, v122

; #define LAS __attribute__((address_space(3)))
; #define LDS_BARRIER() do { asm volatile("s_waitcnt lgkmcnt(0)" ::: "memory"); __builtin_amdgcn_s_barrier(); asm volatile("" ::: "memory"); } while (0)
; #define MFMA32(a, b, c) __builtin_amdgcn_mfma_f32_32x32x16_bf16((a), (b), (c), 0, 0, 0)
; #define NSA_PRIO_ON(c) do { if ((c).hiw) __builtin_amdgcn_s_setprio(3); else __builtin_amdgcn_s_setprio(1); } while (0)
; #define NSA_PRIO_OFF() __builtin_amdgcn_s_setprio(0)
; template <int BR> __device__ __forceinline__ void nsa_softmax_pv(LAS unsigned char* L, int slot, const NsaBr& c, int j, f32x16 (&sa)[2], f32x16 (&oacc)[2], float& mrun, float& lrun) {
;     ...
;     const float msub = (BR == 1 && !mine) ? 1e30f : mrun;
;     f32x2 ps2 = {0.f, 0.f}; float nmsub = -msub; asm volatile("" : "+v"(nmsub)); const f32x2 nm2 = {nmsub, nmsub};
; #pragma unroll
;     for (int kt = 0; kt < 2; ++kt) {
; #pragma unroll
;         for (int i = 0; i < 16; i += 2) { const f32x2 x = (f32x2){sa[kt][i], sa[kt][i + 1]} + nm2; sa[kt][i] = __builtin_amdgcn_exp2f(x.x); sa[kt][i + 1] = __builtin_amdgcn_exp2f(x.y); }
; #pragma unroll
;         for (int i = 0; i < 16; i += 2) ps2 += (f32x2){sa[kt][i], sa[kt][i + 1]};
;     }
;     const float psum = ps2.x + ps2.y;
;     lrun += psum;
;     NSA_PRIO_ON(c);
; #pragma unroll
;     for (int kt = 0; kt < 2; ++kt)
; #pragma unroll
;         for (int s2 = 0; s2 < 2; ++s2) { const bf16x8 pf = pack_step(sa[kt], s2);
; #pragma unroll
;             for (int dt = 0; dt < 2; ++dt) { const LAS unsigned char* vp = L + slot + 9216 + (32 * dt + r) * 136 + (32 * kt + 16 * s2 + 4 * h) * 2;
;                 const s16x4 lo = *(const LAS s16x4*)vp, hi = *(const LAS s16x4*)(vp + 16);
;                 const bf16x8 vf = __builtin_shufflevector(lo, hi, 0, 1, 2, 3, 4, 5, 6, 7);
;                 oacc[dt] = MFMA32(vf, pf, oacc[dt]); } }
;     NSA_PRIO_OFF();
; template <int BR> __device__ __forceinline__ void nsa_step(LAS unsigned char* L, const NsaBr& c, const bf16x8 (&qr)[4], int jj, int nblk, int s_cur, int s_nxt, int s_wr, ...
;     LDS_BARRIER();
;     if (jj + 2 < nblk) { nsa_kv_write(L, s_wr, c, kreg, vreg); if (jj + 3 < nblk) nsa_kv_load(c, c.jlo + jj + 3, kreg, vreg); }
.LBB0_1834:
	v_add_f32_e32 v34, v34, v138
	v_add_f32_e32 v35, v35, v138
	v_add_f32_e32 v36, v36, v138
	v_add_f32_e32 v37, v37, v138
	v_exp_f32_e32 v34, v34
	v_exp_f32_e32 v35, v35
	v_exp_f32_e32 v36, v36
	v_exp_f32_e32 v37, v37
	v_add_f32_e32 v38, v38, v138
	v_add_f32_e32 v39, v39, v138
	v_add_f32_e32 v40, v40, v138
	v_add_f32_e32 v41, v41, v138
	v_exp_f32_e32 v38, v38
	v_exp_f32_e32 v39, v39
	v_exp_f32_e32 v40, v40
	v_exp_f32_e32 v41, v41
	v_add_f32_e32 v42, v42, v138
	v_add_f32_e32 v43, v43, v138
	v_add_f32_e32 v44, v44, v138
	v_add_f32_e32 v45, v45, v138
	v_exp_f32_e32 v42, v42
	v_exp_f32_e32 v43, v43
	v_add_f32_e32 v176, 0, v34
	v_add_f32_e32 v177, 0, v35
	v_exp_f32_e32 v44, v44
	v_exp_f32_e32 v45, v45
	v_add_f32_e32 v46, v46, v138
	v_add_f32_e32 v47, v47, v138
	v_add_f32_e32 v176, v36, v176
	v_add_f32_e32 v177, v37, v177
	v_exp_f32_e32 v46, v46
	v_exp_f32_e32 v47, v47
	v_add_f32_e32 v48, v48, v138
	v_add_f32_e32 v49, v49, v138
	v_add_f32_e32 v176, v38, v176
	v_add_f32_e32 v177, v39, v177
	v_exp_f32_e32 v48, v48
	v_exp_f32_e32 v49, v49
	v_add_f32_e32 v176, v40, v176
	v_add_f32_e32 v177, v41, v177
	v_add_f32_e32 v50, v50, v138
	v_add_f32_e32 v51, v51, v138
	v_add_f32_e32 v176, v42, v176
	v_add_f32_e32 v177, v43, v177
	v_exp_f32_e32 v50, v50
	v_exp_f32_e32 v51, v51
	v_add_f32_e32 v52, v52, v138
	v_add_f32_e32 v53, v53, v138
	v_add_f32_e32 v176, v44, v176
	v_add_f32_e32 v177, v45, v177
	v_exp_f32_e32 v52, v52
	v_exp_f32_e32 v53, v53
	v_add_f32_e32 v54, v54, v138
	v_add_f32_e32 v55, v55, v138
	v_add_f32_e32 v176, v46, v176
	v_add_f32_e32 v177, v47, v177
	v_exp_f32_e32 v54, v54
	v_exp_f32_e32 v55, v55
	v_add_f32_e32 v56, v56, v138
	v_add_f32_e32 v57, v57, v138
	v_add_f32_e32 v176, v48, v176
	v_add_f32_e32 v177, v49, v177
	v_exp_f32_e32 v56, v56
	v_exp_f32_e32 v57, v57
	v_add_f32_e32 v58, v58, v138
	v_add_f32_e32 v59, v59, v138
	v_add_f32_e32 v60, v60, v138
	v_add_f32_e32 v61, v61, v138
	v_exp_f32_e32 v58, v58
	v_exp_f32_e32 v59, v59
	v_add_f32_e32 v176, v50, v176
	v_add_f32_e32 v177, v51, v177
	v_exp_f32_e32 v60, v60
	v_exp_f32_e32 v61, v61
	v_add_f32_e32 v62, v62, v138
	v_add_f32_e32 v63, v63, v138
	v_add_f32_e32 v176, v52, v176
	v_add_f32_e32 v177, v53, v177
	v_exp_f32_e32 v62, v62
	v_exp_f32_e32 v63, v63
	v_add_f32_e32 v64, v64, v138
	v_add_f32_e32 v65, v65, v138
	v_add_f32_e32 v176, v54, v176
	v_add_f32_e32 v177, v55, v177
	v_exp_f32_e32 v64, v64
	v_exp_f32_e32 v65, v65
	v_add_f32_e32 v176, v56, v176
	v_add_f32_e32 v177, v57, v177
	s_add_i32 s0, s7, 0
	v_add_f32_e32 v176, v58, v176
	v_add_f32_e32 v177, v59, v177
	s_nop 0
	v_add_f32_e32 v176, v60, v176
	v_add_f32_e32 v177, v61, v177
	s_nop 0
	v_add_f32_e32 v176, v62, v176
	v_add_f32_e32 v177, v63, v177
	s_nop 0
	v_add_f32_e32 v176, v64, v176
	v_add_f32_e32 v177, v65, v177
	s_nop 0
	v_add_f32_e32 v138, v176, v177
	v_add_f32_e32 v155, v155, v138
	v_add3_u32 v138, s0, v206, v210
	v_add_u32_e32 v175, 0x2000, v138
	v_cvt_pk_bf16_f32 v176, v34, v35
	v_cvt_pk_bf16_f32 v177, v36, v37
	v_cvt_pk_bf16_f32 v178, v38, v39
	v_cvt_pk_bf16_f32 v179, v40, v41
	s_nop 1
	v_add_u32_e32 v138, 0x3000, v138
	ds_read2_b64 v[180:183], v175 offset0:128 offset1:130
	ds_read2_b64 v[252:255], v138 offset0:160 offset1:162
	ds_read2_b64 v[38:41], v175 offset0:132 offset1:134
	s_waitcnt lgkmcnt(2)
	v_mfma_f32_32x32x16_bf16 v[2:17], v[180:183], v[176:179], v[2:17]
	s_waitcnt lgkmcnt(1)
	v_mfma_f32_32x32x16_bf16 v[18:33], v[252:255], v[176:179], v[18:33]
	v_cvt_pk_bf16_f32 v176, v42, v43
	v_cvt_pk_bf16_f32 v177, v44, v45
	v_cvt_pk_bf16_f32 v178, v46, v47
	v_cvt_pk_bf16_f32 v179, v48, v49
	s_nop 1
	ds_read2_b64 v[180:183], v138 offset0:164 offset1:166
	ds_read2_b64 v[252:255], v175 offset0:136 offset1:138
	ds_read2_b64 v[42:45], v138 offset0:168 offset1:170
	s_waitcnt lgkmcnt(3)
	v_mfma_f32_32x32x16_bf16 v[2:17], v[38:41], v[176:179], v[2:17]
	s_waitcnt lgkmcnt(2)
	v_mfma_f32_32x32x16_bf16 v[18:33], v[180:183], v[176:179], v[18:33]
	v_cvt_pk_bf16_f32 v176, v50, v51
	v_cvt_pk_bf16_f32 v177, v52, v53
	v_cvt_pk_bf16_f32 v178, v54, v55
	v_cvt_pk_bf16_f32 v179, v56, v57
	s_nop 1
	ds_read2_b64 v[38:41], v175 offset0:140 offset1:142
	ds_read2_b64 v[180:183], v138 offset0:172 offset1:174
	s_waitcnt lgkmcnt(3)
	v_mfma_f32_32x32x16_bf16 v[2:17], v[252:255], v[176:179], v[2:17]
	s_waitcnt lgkmcnt(2)
	v_mfma_f32_32x32x16_bf16 v[18:33], v[42:45], v[176:179], v[18:33]
	v_cvt_pk_bf16_f32 v176, v58, v59
	v_cvt_pk_bf16_f32 v177, v60, v61
	v_cvt_pk_bf16_f32 v178, v62, v63
	v_cvt_pk_bf16_f32 v179, v64, v65
	s_nop 1
	s_waitcnt lgkmcnt(1)
	v_mfma_f32_32x32x16_bf16 v[2:17], v[38:41], v[176:179], v[2:17]
	s_waitcnt lgkmcnt(0)
	v_mfma_f32_32x32x16_bf16 v[18:33], v[180:183], v[176:179], v[18:33]
	s_setprio 0
	s_andn2_b64 vcc, exec, s[46:47]
	s_cbranch_vccnz .LBB0_1853
	s_waitcnt lgkmcnt(0)
	s_barrier
	s_cmp_gt_i32 s3, s5
	s_cbranch_scc1 .LBB0_1838
	v_add3_u32 v138, s0, v207, v198
	s_waitcnt vmcnt(1)
	ds_write_b128 v138, v[114:117]
	v_add_u32_e32 v138, s0, v208
	v_add3_u32 v138, v138, v198, s13
	s_cmp_gt_i32 s3, s27
	s_waitcnt vmcnt(0)
	ds_write2_b64 v138, v[118:119], v[120:121] offset1:1
	s_cbranch_scc1 .LBB0_1838
	s_add_i32 s0, s26, s4
	s_add_i32 s34, s0, 64
	v_lshl_add_u64 v[114:115], v[130:131], 0, v[198:199]
	v_lshl_add_u64 v[118:119], s[34:35], 1, v[132:133]
	global_load_dwordx4 v[114:117], v[114:115], off
	s_nop 0
	global_load_dwordx4 v[118:121], v[118:119], off offset:384

; template <int BR> __device__ __forceinline__ void nsa_softmax_pv(LAS unsigned char* L, int slot, const NsaBr& c, int j, f32x16 (&sa)[2], f32x16 (&oacc)[2], float& mrun, float& lrun) {
;     ...
;     mblk = fmaxf(mblk, __shfl_xor(mblk, 32));
;     if (__any(mblk > mrun + NSA_DEFER)) {
;         const float mnew = fmaxf(mrun, mblk);
;         const float alpha = __builtin_amdgcn_exp2f(mrun - mnew);
;         lrun *= alpha; mrun = mnew;
; #pragma unroll
;         for (int i = 0; i < 16; ++i) { oacc[0][i] *= alpha; oacc[1][i] *= alpha; }
;     }
;     const float msub = (BR == 1 && !mine) ? 1e30f : mrun;
.LBB0_1846:
	ds_bpermute_b32 v175, v205, v138
	v_max_f32_e32 v138, v138, v138
	s_waitcnt lgkmcnt(0)
	v_max_f32_e32 v175, v175, v175
	v_max_f32_e32 v138, v138, v175
	v_add_f32_e32 v175, 0x41000000, v174
	v_cmp_gt_f32_e32 vcc, v138, v175
	s_cbranch_vccz .LBB0_1848
	v_max_f32_e32 v122, v138, v138
	v_max_f32_e32 v138, v174, v174
	v_max_f32_e32 v138, v138, v122
	v_sub_f32_e32 v122, v174, v138
	v_exp_f32_e32 v122, v122
	v_mov_b32_e32 v174, v138
	v_mul_f32_e32 v155, v155, v122
	v_mul_f32_e32 v32, v32, v122
	v_mul_f32_e32 v33, v33, v122
	v_mul_f32_e32 v30, v30, v122
	v_mul_f32_e32 v31, v31, v122
	v_mul_f32_e32 v28, v28, v122
	v_mul_f32_e32 v29, v29, v122
	v_mul_f32_e32 v26, v26, v122
	v_mul_f32_e32 v27, v27, v122
	v_mul_f32_e32 v24, v24, v122
	v_mul_f32_e32 v25, v25, v122
	v_mul_f32_e32 v22, v22, v122
	v_mul_f32_e32 v23, v23, v122
	v_mul_f32_e32 v20, v20, v122
	v_mul_f32_e32 v21, v21, v122
	v_mul_f32_e32 v18, v18, v122
	v_mul_f32_e32 v19, v19, v122
	v_mul_f32_e32 v16, v16, v122
	v_mul_f32_e32 v17, v17, v122
	v_mul_f32_e32 v14, v14, v122
	v_mul_f32_e32 v15, v15, v122
	v_mul_f32_e32 v12, v12, v122
	v_mul_f32_e32 v13, v13, v122
	v_mul_f32_e32 v10, v10, v122
	v_mul_f32_e32 v11, v11, v122
	v_mul_f32_e32 v8, v8, v122
	v_mul_f32_e32 v9, v9, v122
	v_mul_f32_e32 v6, v6, v122
	v_mul_f32_e32 v7, v7, v122
	v_mul_f32_e32 v4, v4, v122
	v_mul_f32_e32 v5, v5, v122
	v_mul_f32_e32 v2, v2, v122
	v_mul_f32_e32 v3, v3, v122
	v_xor_b32_e32 v122, 0x80000000, v138

; #define LAS __attribute__((address_space(3)))
; #define MFMA32(a, b, c) __builtin_amdgcn_mfma_f32_32x32x16_bf16((a), (b), (c), 0, 0, 0)
; #define NSA_PRIO_ON(c) do { if ((c).hiw) __builtin_amdgcn_s_setprio(3); else __builtin_amdgcn_s_setprio(1); } while (0)
; #define NSA_PRIO_OFF() __builtin_amdgcn_s_setprio(0)
; template <int BR> __device__ __forceinline__ void nsa_softmax_pv(LAS unsigned char* L, int slot, const NsaBr& c, int j, f32x16 (&sa)[2], f32x16 (&oacc)[2], float& mrun, float& lrun) {
;     ...
;     const float msub = (BR == 1 && !mine) ? 1e30f : mrun;
;     f32x2 ps2 = {0.f, 0.f}; float nmsub = -msub; asm volatile("" : "+v"(nmsub)); const f32x2 nm2 = {nmsub, nmsub};
; #pragma unroll
;     for (int kt = 0; kt < 2; ++kt) {
; #pragma unroll
;         for (int i = 0; i < 16; i += 2) { const f32x2 x = (f32x2){sa[kt][i], sa[kt][i + 1]} + nm2; sa[kt][i] = __builtin_amdgcn_exp2f(x.x); sa[kt][i + 1] = __builtin_amdgcn_exp2f(x.y); }
; #pragma unroll
;         for (int i = 0; i < 16; i += 2) ps2 += (f32x2){sa[kt][i], sa[kt][i + 1]};
;     }
;     const float psum = ps2.x + ps2.y;
;     lrun += psum;
;     NSA_PRIO_ON(c);
; #pragma unroll
;     for (int kt = 0; kt < 2; ++kt)
; #pragma unroll
;         for (int s2 = 0; s2 < 2; ++s2) { const bf16x8 pf = pack_step(sa[kt], s2);
; #pragma unroll
;             for (int dt = 0; dt < 2; ++dt) { const LAS unsigned char* vp = L + slot + 9216 + (32 * dt + r) * 136 + (32 * kt + 16 * s2 + 4 * h) * 2;
;                 const s16x4 lo = *(const LAS s16x4*)vp, hi = *(const LAS s16x4*)(vp + 16);
;                 const bf16x8 vf = __builtin_shufflevector(lo, hi, 0, 1, 2, 3, 4, 5, 6, 7);
;                 oacc[dt] = MFMA32(vf, pf, oacc[dt]); } }
;     NSA_PRIO_OFF();
.LBB0_1852:
	v_add_f32_e32 v66, v66, v122
	v_add_f32_e32 v67, v67, v122
	v_add_f32_e32 v68, v68, v122
	v_add_f32_e32 v69, v69, v122
	v_exp_f32_e32 v66, v66
	v_exp_f32_e32 v67, v67
	v_exp_f32_e32 v68, v68
	v_exp_f32_e32 v69, v69
	v_add_f32_e32 v70, v70, v122
	v_add_f32_e32 v71, v71, v122
	v_add_f32_e32 v72, v72, v122
	v_add_f32_e32 v73, v73, v122
	v_exp_f32_e32 v70, v70
	v_exp_f32_e32 v71, v71
	v_exp_f32_e32 v72, v72
	v_exp_f32_e32 v73, v73
	v_add_f32_e32 v74, v74, v122
	v_add_f32_e32 v75, v75, v122
	v_add_f32_e32 v76, v76, v122
	v_add_f32_e32 v77, v77, v122
	v_exp_f32_e32 v74, v74
	v_exp_f32_e32 v75, v75
	v_add_f32_e32 v176, 0, v66
	v_add_f32_e32 v177, 0, v67
	v_exp_f32_e32 v76, v76
	v_exp_f32_e32 v77, v77
	v_add_f32_e32 v78, v78, v122
	v_add_f32_e32 v79, v79, v122
	v_add_f32_e32 v176, v68, v176
	v_add_f32_e32 v177, v69, v177
	v_exp_f32_e32 v78, v78
	v_exp_f32_e32 v79, v79
	v_add_f32_e32 v80, v80, v122
	v_add_f32_e32 v81, v81, v122
	v_add_f32_e32 v176, v70, v176
	v_add_f32_e32 v177, v71, v177
	v_exp_f32_e32 v80, v80
	v_exp_f32_e32 v81, v81
	v_add_f32_e32 v176, v72, v176
	v_add_f32_e32 v177, v73, v177
	v_add_f32_e32 v82, v82, v122
	v_add_f32_e32 v83, v83, v122
	v_add_f32_e32 v176, v74, v176
	v_add_f32_e32 v177, v75, v177
	v_exp_f32_e32 v82, v82
	v_exp_f32_e32 v83, v83
	v_add_f32_e32 v84, v84, v122
	v_add_f32_e32 v85, v85, v122
	v_add_f32_e32 v176, v76, v176
	v_add_f32_e32 v177, v77, v177
	v_exp_f32_e32 v84, v84
	v_exp_f32_e32 v85, v85
	v_add_f32_e32 v86, v86, v122
	v_add_f32_e32 v87, v87, v122
	v_add_f32_e32 v176, v78, v176
	v_add_f32_e32 v177, v79, v177
	v_exp_f32_e32 v86, v86
	v_exp_f32_e32 v87, v87
	v_add_f32_e32 v88, v88, v122
	v_add_f32_e32 v89, v89, v122
	v_add_f32_e32 v176, v80, v176
	v_add_f32_e32 v177, v81, v177
	v_exp_f32_e32 v88, v88
	v_exp_f32_e32 v89, v89
	v_add_f32_e32 v90, v90, v122
	v_add_f32_e32 v91, v91, v122
	v_add_f32_e32 v92, v92, v122
	v_add_f32_e32 v93, v93, v122
	v_exp_f32_e32 v90, v90
	v_exp_f32_e32 v91, v91
	v_add_f32_e32 v176, v82, v176
	v_add_f32_e32 v177, v83, v177
	v_exp_f32_e32 v92, v92
	v_exp_f32_e32 v93, v93
	v_add_f32_e32 v94, v94, v122
	v_add_f32_e32 v95, v95, v122
	v_add_f32_e32 v176, v84, v176
	v_add_f32_e32 v177, v85, v177
	v_exp_f32_e32 v94, v94
	v_exp_f32_e32 v95, v95
	v_add_f32_e32 v96, v96, v122
	v_add_f32_e32 v97, v97, v122
	v_add_f32_e32 v176, v86, v176
	v_add_f32_e32 v177, v87, v177
	v_exp_f32_e32 v96, v96
	v_exp_f32_e32 v97, v97
	v_add_f32_e32 v176, v88, v176
	v_add_f32_e32 v177, v89, v177
	s_nop 0
	v_add_f32_e32 v176, v90, v176
	v_add_f32_e32 v177, v91, v177
	s_nop 0
	v_add_f32_e32 v176, v92, v176
	v_add_f32_e32 v177, v93, v177
	s_nop 0
	v_add_f32_e32 v176, v94, v176
	v_add_f32_e32 v177, v95, v177
	s_nop 0
	v_add_f32_e32 v176, v96, v176
	v_add_f32_e32 v177, v97, v177
	s_nop 0
	v_add_f32_e32 v122, v176, v177
	v_add_f32_e32 v155, v155, v122
	v_add_u32_e32 v122, s50, v211
	v_add_u32_e32 v138, 0x2000, v122
	v_cvt_pk_bf16_f32 v176, v66, v67
	v_cvt_pk_bf16_f32 v177, v68, v69
	v_cvt_pk_bf16_f32 v178, v70, v71
	v_cvt_pk_bf16_f32 v179, v72, v73
	s_nop 1
	v_add_u32_e32 v122, 0x3000, v122
	ds_read2_b64 v[180:183], v138 offset0:128 offset1:130
	ds_read2_b64 v[252:255], v122 offset0:160 offset1:162
	ds_read2_b64 v[70:73], v138 offset0:132 offset1:134
	s_waitcnt lgkmcnt(2)
	v_mfma_f32_32x32x16_bf16 v[2:17], v[180:183], v[176:179], v[2:17]
	s_waitcnt lgkmcnt(1)
	v_mfma_f32_32x32x16_bf16 v[18:33], v[252:255], v[176:179], v[18:33]
	v_cvt_pk_bf16_f32 v176, v74, v75
	v_cvt_pk_bf16_f32 v177, v76, v77
	v_cvt_pk_bf16_f32 v178, v78, v79
	v_cvt_pk_bf16_f32 v179, v80, v81
	s_nop 1
	ds_read2_b64 v[180:183], v122 offset0:164 offset1:166
	ds_read2_b64 v[252:255], v138 offset0:136 offset1:138
	ds_read2_b64 v[74:77], v122 offset0:168 offset1:170
	s_waitcnt lgkmcnt(3)
	v_mfma_f32_32x32x16_bf16 v[2:17], v[70:73], v[176:179], v[2:17]
	s_waitcnt lgkmcnt(2)
	v_mfma_f32_32x32x16_bf16 v[18:33], v[180:183], v[176:179], v[18:33]
	v_cvt_pk_bf16_f32 v176, v82, v83
	v_cvt_pk_bf16_f32 v177, v84, v85
	v_cvt_pk_bf16_f32 v178, v86, v87
	v_cvt_pk_bf16_f32 v179, v88, v89
	s_nop 1
	ds_read2_b64 v[70:73], v138 offset0:140 offset1:142
	ds_read2_b64 v[180:183], v122 offset0:172 offset1:174
	s_waitcnt lgkmcnt(3)
	v_mfma_f32_32x32x16_bf16 v[2:17], v[252:255], v[176:179], v[2:17]
	s_waitcnt lgkmcnt(2)
	v_mfma_f32_32x32x16_bf16 v[18:33], v[74:77], v[176:179], v[18:33]
	v_cvt_pk_bf16_f32 v176, v90, v91
	v_cvt_pk_bf16_f32 v177, v92, v93
	v_cvt_pk_bf16_f32 v178, v94, v95
	v_cvt_pk_bf16_f32 v179, v96, v97
	s_nop 1
	s_waitcnt lgkmcnt(1)
	v_mfma_f32_32x32x16_bf16 v[2:17], v[70:73], v[176:179], v[2:17]
	s_waitcnt lgkmcnt(0)
	v_mfma_f32_32x32x16_bf16 v[18:33], v[180:183], v[176:179], v[18:33]
	s_setprio 0
